# P2 pre- and post-stage loads hoisted (hazard-distance preserving, loads-only vmcnt) on top of MLP-first stack
# baseline (speedup 1.0000x reference)
; #define LAS __attribute__((address_space(3)))
; __device__ __forceinline__ unsigned pk2(float lo, float hi) { unsigned r; asm("v_cvt_pk_bf16_f32 %0, %1, %2" : "=v"(r) : "v"(lo), "v"(hi)); return r; }
; __device__ __forceinline__ float bflo(unsigned w) { return __uint_as_float(w << 16); }
; __device__ __forceinline__ float bfhi(unsigned w) { return __uint_as_float(w & 0xffff0000u); }
; __device__ __forceinline__ float bf1(bf16 h) { return __uint_as_float((unsigned)h << 16); }
; __device__ __forceinline__ void conv8(const bf16* row, int p0, float c0, float c1, float c2, float cb, float (&o)[8]) {
;     const v4u w = *(const v4u*)(row + p0);
;     float x[10];
;     x[0] = bf1(row[p0 > 0 ? p0 - 1 : 0]) * (p0 > 0 ? 1.f : 0.f); x[9] = bf1(row[p0 + 8 < SEQL ? p0 + 8 : SEQL - 1]) * (p0 + 8 < SEQL ? 1.f : 0.f);
;     x[1] = bflo(w.x); x[2] = bfhi(w.x); x[3] = bflo(w.y); x[4] = bfhi(w.y); x[5] = bflo(w.z); x[6] = bfhi(w.z); x[7] = bflo(w.w); x[8] = bfhi(w.w);
; #pragma unroll
;     for (int e = 0; e < 8; ++e) o[e] = c0 * x[e] + c1 * x[e + 1] + c2 * x[e + 2] + cb;
; }
; template <int VAR> __device__ __forceinline__ void hyena_conv_phase(const Frame& F, const bf16* ZT, const bf16* GT, const float* conv_w, const float* conv_b, const float* skip, float* gscr, float* zscr, bf16* UT) {
;     ...
;         __syncthreads();
;         int te = t0; asm volatile("" : "+v"(te));
; #pragma unroll
;         for (int qi = 0; qi < 8; ++qi) { const int q = te + 512 * qi; const int b = qi >> 2, p0 = (q & 2047) * 8; float c0[8];
;             conv8(rx0 + b * SEQL, p0, a0, a1, a2, ab, c0);
;             const f32x4 y0 = *(LAS f32x4*)(X + b * SEQL + p0), y1 = *(LAS f32x4*)(X + b * SEQL + p0 + 4);
;             float u[8];
; #pragma unroll
;             for (int e = 0; e < 4; ++e) { u[e] = y0[e] * c0[e]; u[4 + e] = y1[e] * c0[4 + e]; }
;             v4u o; o.x = pk2(u[0], u[1]); o.y = pk2(u[2], u[3]); o.z = pk2(u[4], u[5]); o.w = pk2(u[6], u[7]);
;             *(v4u*)(UT + (size_t)c * MTOK + b * SEQL + p0) = o; }
.LBB0_322:
	v_mov_b32_e32 v0, v221
	s_waitcnt lgkmcnt(0)
	s_barrier
	s_lshl_b64 s[6:7], s[82:83], 1
	v_lshlrev_b32_e32 v9, 3, v0
	v_and_b32_e32 v8, 0x3ff8, v9
	s_add_u32 s88, s40, s6
	v_sub_u32_e64 v0, v8, 1 clamp
	s_addc_u32 s89, s41, s7
	v_lshlrev_b32_e32 v16, 1, v8
	v_lshlrev_b32_e32 v11, 1, v0
	v_min_u32_e32 v0, 0x3ff7, v8
	global_load_dwordx4 v[4:7], v16, s[88:89]
	v_lshlrev_b32_e32 v27, 1, v0
	global_load_ushort v36, v27, s[88:89] offset:16
	global_load_ushort v26, v11, s[88:89]
	v_add_u32_e32 v0, 0x1000, v9
	v_and_b32_e32 v10, 0x3ff8, v0
	v_sub_u32_e64 v0, v10, 1 clamp
	v_lshlrev_b32_e32 v52, 1, v0
	global_load_ushort v53, v52, s[88:89]
	v_lshlrev_b32_e32 v32, 1, v10
	global_load_dwordx4 v[12:15], v32, s[88:89]
	s_add_u32 s82, s12, s6
	s_addc_u32 s83, s13, s7
	v_min_u32_e32 v0, 0x3ff7, v10
	s_add_u32 s6, s88, 0x8000
	v_lshlrev_b32_e32 v55, 1, v0
	v_mov_b32_e32 v21, v18
	v_cmp_eq_u32_e32 vcc, 0, v8
	s_addc_u32 s7, s89, 0
	global_load_ushort v56, v55, s[88:89] offset:16
	global_load_dwordx4 v[0:3], v16, s[6:7]
	global_load_ushort v35, v27, s[6:7] offset:16
	global_load_ushort v37, v11, s[6:7]
	global_load_ushort v88, v55, s[6:7] offset:16
	global_load_ushort v90, v52, s[6:7]
	global_load_dwordx4 v[70:73], v32, s[6:7]
	v_bitop3_b32 v218, v9, s87, v160 bitop3:0x6c
	v_lshlrev_b32_e32 v219, 1, v218
	global_load_dwordx4 v[74:77], v219, s[88:89]
	v_bitop3_b32 v218, v9, s87, v160 bitop3:0x6c
	v_sub_u32_e64 v219, v218, 1 clamp
	v_lshlrev_b32_e32 v230, 1, v219
	global_load_ushort v92, v230, s[88:89]
	v_bitop3_b32 v218, v9, s87, v160 bitop3:0x6c
	v_min_u32_e32 v219, 0x3ff7, v218
	v_lshlrev_b32_e32 v230, 1, v219
	global_load_ushort v94, v230, s[88:89] offset:16
	v_add_u32_e32 v218, 0x3000, v9
	v_and_b32_e32 v219, 0x3ff8, v218
	v_sub_u32_e64 v230, v219, 1 clamp
	v_lshlrev_b32_e32 v232, 1, v230
	global_load_ushort v96, v232, s[88:89]
	v_bitop3_b32 v218, v9, s87, v160 bitop3:0x6c
	v_min_u32_e32 v219, 0x3ff7, v218
	v_lshlrev_b32_e32 v230, 1, v219
	global_load_ushort v98, v230, s[6:7] offset:16
	v_bitop3_b32 v218, v9, s87, v160 bitop3:0x6c
	v_sub_u32_e64 v219, v218, 1 clamp
	v_lshlrev_b32_e32 v230, 1, v219
	global_load_ushort v100, v230, s[6:7]
	v_add_u32_e32 v218, 0x3000, v9
	v_and_b32_e32 v219, 0x3ff8, v218
	v_lshlrev_b32_e32 v230, 1, v219
	global_load_dwordx4 v[78:81], v230, s[88:89]
	v_add_u32_e32 v218, 0x3000, v9
	v_and_b32_e32 v219, 0x3ff8, v218
	v_min_u32_e32 v230, 0x3ff7, v219
	v_lshlrev_b32_e32 v232, 1, v230
	global_load_ushort v102, v232, s[88:89] offset:16
	v_bitop3_b32 v218, v9, s87, v160 bitop3:0x6c
	v_lshlrev_b32_e32 v219, 1, v218
	global_load_dwordx4 v[82:85], v219, s[6:7]
	v_add_u32_e32 v218, 0x3000, v9
	v_and_b32_e32 v219, 0x3ff8, v218
	v_min_u32_e32 v230, 0x3ff7, v219
	v_lshlrev_b32_e32 v232, 1, v230
	global_load_ushort v104, v232, s[6:7] offset:16
	v_add_u32_e32 v218, 0x3000, v9
	v_and_b32_e32 v219, 0x3ff8, v218
	v_sub_u32_e64 v230, v219, 1 clamp
	v_lshlrev_b32_e32 v232, 1, v230
	global_load_ushort v106, v232, s[6:7]
	v_add_u32_e32 v218, 0x3000, v9
	v_and_b32_e32 v219, 0x3ff8, v218
	v_lshlrev_b32_e32 v230, 1, v219
	global_load_dwordx4 v[134:137], v230, s[6:7]
	v_mov_b32_e32 v22, v18
	v_mov_b32_e32 v23, v20
	v_cndmask_b32_e64 v34, 1.0, 0, vcc
	v_cmp_eq_u32_e32 vcc, s11, v8
	v_mov_b32_e32 v24, v20
	v_lshlrev_b32_e32 v33, 2, v8
	v_cndmask_b32_e64 v25, 1.0, 0, vcc
	v_add_u32_e32 v54, 0, v33
	v_cmp_eq_u32_e32 vcc, 0, v10
	v_lshlrev_b32_e32 v58, 2, v10
	v_add_u32_e32 v33, s85, v33
	s_waitcnt vmcnt(23)
	v_lshlrev_b32_e32 v27, 16, v4
	v_and_b32_e32 v29, 0xffff0000, v5
	v_and_b32_e32 v28, 0xffff0000, v4
	v_lshlrev_b32_e32 v4, 16, v5
	v_lshlrev_b32_e32 v5, 16, v6
	v_and_b32_e32 v30, 0xffff0000, v6
	v_lshlrev_b32_e32 v6, 16, v7
	v_and_b32_e32 v31, 0xffff0000, v7
	s_waitcnt vmcnt(21)
	v_lshlrev_b32_e32 v11, 16, v26
	v_mov_b32_e32 v26, v28
	v_pk_mul_f32 v[38:39], v[20:21], v[28:29]
	v_mov_b32_e32 v40, v4
	v_mov_b32_e32 v41, v28
	v_pk_mul_f32 v[42:43], v[20:21], v[4:5]
	v_mov_b32_e32 v28, v30
	v_mov_b32_e32 v46, v6
	v_mov_b32_e32 v47, v30
	v_pk_mul_f32 v[44:45], v[20:21], v[30:31]
	v_lshlrev_b32_e32 v7, 16, v36
	v_mul_f32_e32 v11, v34, v11
	v_pk_mul_f32 v[48:49], v[18:19], v[26:27]
	v_pk_mul_f32 v[40:41], v[18:19], v[40:41]
	v_fma_f32 v4, v19, v4, v38
	v_fma_f32 v26, v19, v29, v42
	v_pk_mul_f32 v[28:29], v[22:23], v[28:29]
	v_pk_mul_f32 v[46:47], v[18:19], v[46:47]
	v_fma_f32 v30, v19, v6, v44
	v_pk_mul_f32 v[50:51], v[24:25], v[6:7]
	v_fma_f32 v6, v20, v11, v49
	v_fma_f32 v7, v20, v27, v41
	v_add_f32_e32 v4, v39, v4
	v_add_f32_e32 v11, v43, v26
	v_fma_f32 v26, v19, v5, v29
	v_fma_f32 v5, v20, v5, v47
	v_add_f32_e32 v27, v45, v30
	v_add_f32_e32 v6, v48, v6
	v_add_f32_e32 v7, v40, v7
	v_add_f32_e32 v30, v193, v4
	v_add_f32_e32 v4, v28, v26
	v_add_f32_e32 v5, v46, v5
	v_add_f32_e32 v36, v193, v27
	v_add_f32_e32 v38, v193, v6
	v_add_f32_e32 v39, v193, v7
	v_add_f32_e32 v40, v193, v4
	v_add_f32_e32 v41, v193, v5
	ds_read_b128 v[4:7], v54
	ds_read_b128 v[26:29], v54 offset:16
	v_fma_f32 v31, v19, v31, v50
	v_add_f32_e32 v11, v193, v11
	v_fmac_f32_e32 v31, v18, v51
	v_add_f32_e32 v31, v193, v31
	s_waitcnt lgkmcnt(1)
	v_mul_f32_e32 v4, v4, v38
	v_mul_f32_e32 v5, v5, v39
	v_mul_f32_e32 v6, v6, v30
	v_mul_f32_e32 v7, v7, v11
	s_waitcnt lgkmcnt(0)
	v_mul_f32_e32 v26, v26, v40
	v_mul_f32_e32 v27, v27, v41
	v_mul_f32_e32 v28, v28, v36
	v_mul_f32_e32 v11, v29, v31
	v_cvt_pk_bf16_f32 v4, v4, v5
	v_cvt_pk_bf16_f32 v5, v6, v7
	v_cvt_pk_bf16_f32 v6, v26, v27
	v_cvt_pk_bf16_f32 v7, v28, v11
	global_store_dwordx4 v16, v[4:7], s[82:83]
	s_nop 0
	s_nop 0
	s_waitcnt vmcnt(20)
; #define LAS __attribute__((address_space(3)))
; __device__ __forceinline__ unsigned pk2(float lo, float hi) { unsigned r; asm("v_cvt_pk_bf16_f32 %0, %1, %2" : "=v"(r) : "v"(lo), "v"(hi)); return r; }
; __device__ __forceinline__ float bflo(unsigned w) { return __uint_as_float(w << 16); }
; __device__ __forceinline__ float bfhi(unsigned w) { return __uint_as_float(w & 0xffff0000u); }
; __device__ __forceinline__ float bf1(bf16 h) { return __uint_as_float((unsigned)h << 16); }
; __device__ __forceinline__ void conv8(const bf16* row, int p0, float c0, float c1, float c2, float cb, float (&o)[8]) {
;     const v4u w = *(const v4u*)(row + p0);
;     float x[10];
;     x[0] = bf1(row[p0 > 0 ? p0 - 1 : 0]) * (p0 > 0 ? 1.f : 0.f); x[9] = bf1(row[p0 + 8 < SEQL ? p0 + 8 : SEQL - 1]) * (p0 + 8 < SEQL ? 1.f : 0.f);
;     x[1] = bflo(w.x); x[2] = bfhi(w.x); x[3] = bflo(w.y); x[4] = bfhi(w.y); x[5] = bflo(w.z); x[6] = bfhi(w.z); x[7] = bflo(w.w); x[8] = bfhi(w.w);
; #pragma unroll
;     for (int e = 0; e < 8; ++e) o[e] = c0 * x[e] + c1 * x[e + 1] + c2 * x[e + 2] + cb;
; }
; template <int VAR> __device__ __forceinline__ void hyena_conv_phase(const Frame& F, const bf16* ZT, const bf16* GT, const float* conv_w, const float* conv_b, const float* skip, float* gscr, float* zscr, bf16* UT) {
;     ...
;         int te = t0; asm volatile("" : "+v"(te));
; #pragma unroll
;         for (int qi = 0; qi < 8; ++qi) { const int q = te + 512 * qi; const int b = qi >> 2, p0 = (q & 2047) * 8; float c0[8];
;             conv8(rx0 + b * SEQL, p0, a0, a1, a2, ab, c0);
;             const f32x4 y0 = *(LAS f32x4*)(X + b * SEQL + p0), y1 = *(LAS f32x4*)(X + b * SEQL + p0 + 4);
;             float u[8];
; #pragma unroll
;             for (int e = 0; e < 4; ++e) { u[e] = y0[e] * c0[e]; u[4 + e] = y1[e] * c0[4 + e]; }
;             v4u o; o.x = pk2(u[0], u[1]); o.y = pk2(u[2], u[3]); o.z = pk2(u[4], u[5]); o.w = pk2(u[6], u[7]);
;             *(v4u*)(UT + (size_t)c * MTOK + b * SEQL + p0) = o; }
	v_lshlrev_b32_e32 v4, 16, v53
	v_cndmask_b32_e64 v52, 1.0, 0, vcc
	v_bitop3_b32 v48, v9, s87, v160 bitop3:0x6c
	v_mul_f32_e32 v11, v52, v4
	v_sub_u32_e64 v4, v48, 1 clamp
	v_lshlrev_b32_e32 v36, 1, v48
	v_lshlrev_b32_e32 v46, 1, v4
	s_nop 0
	s_nop 0
	s_nop 0
	s_waitcnt vmcnt(19)
	v_and_b32_e32 v30, 0xffff0000, v12
	v_lshlrev_b32_e32 v29, 16, v12
	v_mov_b32_e32 v28, v30
	v_pk_mul_f32 v[42:43], v[18:19], v[28:29]
	v_lshlrev_b32_e32 v12, 16, v13
	v_fma_f32 v11, v20, v11, v43
	v_mov_b32_e32 v44, v12
	v_mov_b32_e32 v45, v30
	v_add_f32_e32 v11, v42, v11
	v_pk_mul_f32 v[44:45], v[18:19], v[44:45]
	v_and_b32_e32 v31, 0xffff0000, v13
	v_add_f32_e32 v49, v193, v11
	v_fma_f32 v11, v20, v29, v45
	v_pk_mul_f32 v[42:43], v[20:21], v[30:31]
	v_add_f32_e32 v11, v44, v11
	v_lshlrev_b32_e32 v13, 16, v14
	v_add_f32_e32 v44, v193, v11
	v_fma_f32 v11, v19, v12, v42
	v_add_f32_e32 v11, v43, v11
	v_pk_mul_f32 v[28:29], v[20:21], v[12:13]
	v_and_b32_e32 v42, 0xffff0000, v14
	v_add_f32_e32 v45, v193, v11
	v_fma_f32 v11, v19, v31, v28
	v_mov_b32_e32 v30, v42
	v_add_f32_e32 v11, v29, v11
	v_pk_mul_f32 v[28:29], v[22:23], v[30:31]
	v_lshlrev_b32_e32 v14, 16, v15
	v_add_f32_e32 v53, v193, v11
	v_fma_f32 v11, v19, v13, v29
	v_mov_b32_e32 v30, v14
	v_mov_b32_e32 v31, v42
	v_add_f32_e32 v11, v28, v11
	v_pk_mul_f32 v[30:31], v[18:19], v[30:31]
	v_and_b32_e32 v43, 0xffff0000, v15
	v_add_f32_e32 v54, v193, v11
	v_fma_f32 v11, v20, v13, v31
	v_pk_mul_f32 v[28:29], v[20:21], v[42:43]
	v_add_f32_e32 v11, v30, v11
	s_waitcnt vmcnt(18)
	v_lshlrev_b32_e32 v15, 16, v56
	v_min_u32_e32 v12, 0x3ff7, v48
	v_add_f32_e32 v56, v193, v11
	v_fma_f32 v11, v19, v14, v28
	v_lshlrev_b32_e32 v42, 1, v12
	v_add_f32_e32 v11, v29, v11
	v_add_u32_e32 v28, 0, v58
	v_cmp_eq_u32_e32 vcc, s11, v10
	s_nop 0
	v_add_f32_e32 v57, v193, v11
	ds_read_b128 v[10:13], v28
	ds_read_b128 v[28:31], v28 offset:16
	v_cndmask_b32_e64 v27, 1.0, 0, vcc
	v_mov_b32_e32 v26, v20
	v_pk_mul_f32 v[14:15], v[26:27], v[14:15]
	v_add_u32_e32 v9, 0x3000, v9
	v_fma_f32 v14, v19, v43, v14
	v_fmac_f32_e32 v14, v18, v15
	s_waitcnt lgkmcnt(1)
	v_mul_f32_e32 v13, v13, v53
	v_and_b32_e32 v53, 0x3ff8, v9
	v_add_f32_e32 v14, v193, v14
	v_mul_f32_e32 v10, v10, v49
	v_mul_f32_e32 v11, v11, v44
	v_mul_f32_e32 v12, v12, v45
	v_sub_u32_e64 v9, v53, 1 clamp
	s_waitcnt lgkmcnt(0)
	v_mul_f32_e32 v15, v28, v54
	v_mul_f32_e32 v28, v29, v56
	v_mul_f32_e32 v29, v30, v57
	v_mul_f32_e32 v14, v31, v14
	v_cvt_pk_bf16_f32 v10, v10, v11
	v_cvt_pk_bf16_f32 v11, v12, v13
	v_cvt_pk_bf16_f32 v12, v15, v28
	v_cvt_pk_bf16_f32 v13, v29, v14
	global_store_dwordx4 v32, v[10:13], s[82:83]
	v_lshlrev_b32_e32 v49, 1, v9
	v_lshlrev_b32_e32 v60, 1, v53
	s_nop 0
	s_nop 0
	s_nop 0
	v_cmp_eq_u32_e32 vcc, s87, v8
	s_nop 0
	v_lshlrev_b32_e32 v68, 2, v48
	v_cndmask_b32_e64 v59, 1.0, 0, vcc
	s_waitcnt vmcnt(11)
	s_nop 1
	v_mov_b32_e32 v50, v88
	v_mov_b32_e32 v51, v90
	v_mov_b32_e32 v4, v70
	v_mov_b32_e32 v5, v71
	v_mov_b32_e32 v6, v72
	v_mov_b32_e32 v7, v73
	v_mov_b32_e32 v38, v74
	v_mov_b32_e32 v39, v75
	v_mov_b32_e32 v40, v76
	v_mov_b32_e32 v41, v77
	v_and_b32_e32 v14, 0xffff0000, v38
	s_waitcnt vmcnt(10)
	s_nop 1
	v_mov_b32_e32 v47, v92
	v_lshlrev_b32_e32 v9, 16, v47
	v_lshlrev_b32_e32 v13, 16, v38
	v_mov_b32_e32 v12, v14
	v_mul_f32_e32 v28, v59, v9
	v_pk_mul_f32 v[30:31], v[18:19], v[12:13]
	v_lshlrev_b32_e32 v38, 16, v39
	v_fma_f32 v12, v20, v28, v31
	v_mov_b32_e32 v46, v38
	v_mov_b32_e32 v47, v14
	v_add_f32_e32 v12, v30, v12
	v_pk_mul_f32 v[46:47], v[18:19], v[46:47]
	v_and_b32_e32 v15, 0xffff0000, v39
	v_add_f32_e32 v61, v193, v12
	v_fma_f32 v12, v20, v13, v47
	v_pk_mul_f32 v[30:31], v[20:21], v[14:15]
	v_add_f32_e32 v12, v46, v12
	v_add_f32_e32 v62, v193, v12
	v_fma_f32 v12, v19, v38, v30
	v_lshlrev_b32_e32 v39, 16, v40
	v_add_f32_e32 v12, v31, v12
	v_add_f32_e32 v63, v193, v12
	v_pk_mul_f32 v[12:13], v[20:21], v[38:39]
	v_and_b32_e32 v30, 0xffff0000, v40
	v_fma_f32 v12, v19, v15, v12
	v_add_f32_e32 v12, v13, v12
	v_mov_b32_e32 v14, v30
	v_add_f32_e32 v64, v193, v12
	v_pk_mul_f32 v[12:13], v[22:23], v[14:15]
	v_min_u32_e32 v14, 0x3ff7, v53
	v_lshlrev_b32_e32 v65, 1, v14
	s_nop 0
	v_lshlrev_b32_e32 v14, 16, v41
	v_and_b32_e32 v31, 0xffff0000, v41
	v_fma_f32 v13, v19, v39, v13
	v_mov_b32_e32 v40, v14
	v_mov_b32_e32 v41, v30
	v_add_f32_e32 v12, v12, v13
	v_pk_mul_f32 v[40:41], v[18:19], v[40:41]
	v_add_f32_e32 v67, v193, v12
	v_pk_mul_f32 v[12:13], v[20:21], v[30:31]
	v_fma_f32 v28, v20, v39, v41
	v_cmp_eq_u32_e32 vcc, s33, v8
	s_nop 0
	v_add_f32_e32 v28, v40, v28
	v_fma_f32 v12, v19, v14, v12
	v_cndmask_b32_e64 v29, 1.0, 0, vcc
	v_add_f32_e32 v30, v193, v28
	s_waitcnt vmcnt(9)
	s_nop 1
	v_mov_b32_e32 v55, v94
	v_lshlrev_b32_e32 v15, 16, v55
	v_add_f32_e32 v12, v13, v12
	v_mov_b32_e32 v28, v20
	v_add_u32_e32 v38, 0, v68
	v_add_f32_e32 v55, v193, v12
	v_pk_mul_f32 v[46:47], v[28:29], v[14:15]
	ds_read_b128 v[12:15], v38
	ds_read_b128 v[38:41], v38 offset:16
	v_fma_f32 v31, v19, v31, v46
	v_fmac_f32_e32 v31, v18, v47
	v_add_f32_e32 v31, v193, v31
	s_waitcnt lgkmcnt(1)
	v_mul_f32_e32 v12, v12, v61
	s_waitcnt lgkmcnt(0)
	v_mul_f32_e32 v38, v38, v67
	v_mul_f32_e32 v13, v13, v62
	v_mul_f32_e32 v30, v39, v30
	v_mul_f32_e32 v14, v14, v63
	v_mul_f32_e32 v39, v40, v55
	v_mul_f32_e32 v15, v15, v64
	v_cvt_pk_bf16_f32 v12, v12, v13
	v_cmp_eq_u32_e32 vcc, 0, v53
	v_mul_f32_e32 v31, v41, v31
	v_cvt_pk_bf16_f32 v13, v14, v15
	v_cvt_pk_bf16_f32 v14, v38, v30
	v_cvt_pk_bf16_f32 v15, v39, v31
	global_store_dwordx4 v36, v[12:15], s[82:83]
	s_nop 0
	s_nop 0
	s_waitcnt vmcnt(8)
	s_nop 1
	v_mov_b32_e32 v54, v96
	v_lshlrev_b32_e32 v12, 16, v54
	v_cndmask_b32_e64 v54, 1.0, 0, vcc
	v_mul_f32_e32 v30, v54, v12
	v_cmp_eq_u32_e32 vcc, s11, v53
	s_waitcnt vmcnt(5)
; #define LAS __attribute__((address_space(3)))
; __device__ __forceinline__ unsigned pk2(float lo, float hi) { unsigned r; asm("v_cvt_pk_bf16_f32 %0, %1, %2" : "=v"(r) : "v"(lo), "v"(hi)); return r; }
; __device__ __forceinline__ float bflo(unsigned w) { return __uint_as_float(w << 16); }
; __device__ __forceinline__ float bfhi(unsigned w) { return __uint_as_float(w & 0xffff0000u); }
; __device__ __forceinline__ float bf1(bf16 h) { return __uint_as_float((unsigned)h << 16); }
; __device__ __forceinline__ void conv8(const bf16* row, int p0, float c0, float c1, float c2, float cb, float (&o)[8]) {
;     const v4u w = *(const v4u*)(row + p0);
;     float x[10];
;     x[0] = bf1(row[p0 > 0 ? p0 - 1 : 0]) * (p0 > 0 ? 1.f : 0.f); x[9] = bf1(row[p0 + 8 < SEQL ? p0 + 8 : SEQL - 1]) * (p0 + 8 < SEQL ? 1.f : 0.f);
;     x[1] = bflo(w.x); x[2] = bfhi(w.x); x[3] = bflo(w.y); x[4] = bfhi(w.y); x[5] = bflo(w.z); x[6] = bfhi(w.z); x[7] = bflo(w.w); x[8] = bfhi(w.w);
; #pragma unroll
;     for (int e = 0; e < 8; ++e) o[e] = c0 * x[e] + c1 * x[e + 1] + c2 * x[e + 2] + cb;
; }
; template <int VAR> __device__ __forceinline__ void hyena_conv_phase(const Frame& F, const bf16* ZT, const bf16* GT, const float* conv_w, const float* conv_b, const float* skip, float* gscr, float* zscr, bf16* UT) {
;     ...
;         int te = t0; asm volatile("" : "+v"(te));
; #pragma unroll
;         for (int qi = 0; qi < 8; ++qi) { const int q = te + 512 * qi; const int b = qi >> 2, p0 = (q & 2047) * 8; float c0[8];
;             conv8(rx0 + b * SEQL, p0, a0, a1, a2, ab, c0);
;             const f32x4 y0 = *(LAS f32x4*)(X + b * SEQL + p0), y1 = *(LAS f32x4*)(X + b * SEQL + p0 + 4);
;             float u[8];
; #pragma unroll
;             for (int e = 0; e < 4; ++e) { u[e] = y0[e] * c0[e]; u[4 + e] = y1[e] * c0[4 + e]; }
;             v4u o; o.x = pk2(u[0], u[1]); o.y = pk2(u[2], u[3]); o.z = pk2(u[4], u[5]); o.w = pk2(u[6], u[7]);
;             *(v4u*)(UT + (size_t)c * MTOK + b * SEQL + p0) = o; }
	s_nop 1
	v_mov_b32_e32 v56, v98
	v_mov_b32_e32 v57, v100
	v_mov_b32_e32 v42, v78
	v_mov_b32_e32 v43, v79
	v_mov_b32_e32 v44, v80
	v_mov_b32_e32 v45, v81
	v_and_b32_e32 v40, 0xffff0000, v42
	v_lshlrev_b32_e32 v39, 16, v42
	v_mov_b32_e32 v38, v40
	v_pk_mul_f32 v[46:47], v[18:19], v[38:39]
	v_lshlrev_b32_e32 v42, 16, v43
	v_fma_f32 v30, v20, v30, v47
	v_mov_b32_e32 v48, v42
	v_mov_b32_e32 v49, v40
	v_add_f32_e32 v30, v46, v30
	v_pk_mul_f32 v[48:49], v[18:19], v[48:49]
	v_and_b32_e32 v41, 0xffff0000, v43
	v_add_f32_e32 v62, v193, v30
	v_fma_f32 v30, v20, v39, v49
	v_pk_mul_f32 v[46:47], v[20:21], v[40:41]
	v_add_f32_e32 v30, v48, v30
	v_lshlrev_b32_e32 v43, 16, v44
	v_add_f32_e32 v63, v193, v30
	v_fma_f32 v30, v19, v42, v46
	v_add_f32_e32 v30, v47, v30
	v_pk_mul_f32 v[38:39], v[20:21], v[42:43]
	v_and_b32_e32 v46, 0xffff0000, v44
	v_add_f32_e32 v64, v193, v30
	v_fma_f32 v30, v19, v41, v38
	v_mov_b32_e32 v40, v46
	v_add_f32_e32 v30, v39, v30
	v_pk_mul_f32 v[38:39], v[22:23], v[40:41]
	v_lshlrev_b32_e32 v40, 16, v45
	v_add_f32_e32 v65, v193, v30
	v_and_b32_e32 v47, 0xffff0000, v45
	v_fma_f32 v30, v19, v43, v39
	v_mov_b32_e32 v44, v40
	v_mov_b32_e32 v45, v46
	v_add_f32_e32 v30, v38, v30
	v_pk_mul_f32 v[44:45], v[18:19], v[44:45]
	v_add_f32_e32 v67, v193, v30
	v_fma_f32 v30, v20, v43, v45
	v_pk_mul_f32 v[38:39], v[20:21], v[46:47]
	v_add_f32_e32 v30, v44, v30
	v_add_f32_e32 v46, v193, v30
	v_fma_f32 v30, v19, v40, v38
	v_add_f32_e32 v30, v39, v30
	v_lshlrev_b32_e32 v53, 2, v53
	v_cndmask_b32_e64 v31, 1.0, 0, vcc
	s_waitcnt vmcnt(4)
	s_nop 1
	v_mov_b32_e32 v66, v102
	v_lshlrev_b32_e32 v41, 16, v66
	v_add_f32_e32 v66, v193, v30
	v_mov_b32_e32 v30, v20
	v_add_u32_e32 v42, 0, v53
	s_nop 0
	v_pk_mul_f32 v[48:49], v[30:31], v[40:41]
	ds_read_b128 v[38:41], v42
	ds_read_b128 v[42:45], v42 offset:16
	v_fma_f32 v47, v19, v47, v48
	v_fmac_f32_e32 v47, v18, v49
	v_add_f32_e32 v47, v193, v47
	s_waitcnt lgkmcnt(1)
	v_mul_f32_e32 v38, v38, v62
	v_mul_f32_e32 v39, v39, v63
	v_mul_f32_e32 v40, v40, v64
	s_waitcnt lgkmcnt(0)
	v_mul_f32_e32 v42, v42, v67
	v_mul_f32_e32 v43, v43, v46
	v_mul_f32_e32 v41, v41, v65
	v_cvt_pk_bf16_f32 v38, v38, v39
	v_cvt_pk_bf16_f32 v39, v40, v41
	v_cvt_pk_bf16_f32 v40, v42, v43
	v_mul_f32_e32 v44, v44, v66
	v_mul_f32_e32 v45, v45, v47
	v_cvt_pk_bf16_f32 v41, v44, v45
	global_store_dwordx4 v60, v[38:41], s[82:83]
	v_lshlrev_b32_e32 v37, 16, v37
	v_mul_f32_e32 v34, v34, v37
	v_and_b32_e32 v40, 0xffff0000, v0
	v_lshlrev_b32_e32 v39, 16, v0
	v_mov_b32_e32 v38, v40
	v_pk_mul_f32 v[42:43], v[18:19], v[38:39]
	v_mov_b32_e32 v45, v40
	v_fma_f32 v0, v20, v34, v43
	v_add_f32_e32 v0, v42, v0
	v_add_f32_e32 v37, v193, v0
	v_lshlrev_b32_e32 v0, 16, v1
	v_mov_b32_e32 v44, v0
	v_pk_mul_f32 v[44:45], v[18:19], v[44:45]
	v_and_b32_e32 v41, 0xffff0000, v1
	v_fma_f32 v34, v20, v39, v45
	v_pk_mul_f32 v[42:43], v[20:21], v[40:41]
	v_lshlrev_b32_e32 v1, 16, v2
	v_add_f32_e32 v34, v44, v34
	v_add_f32_e32 v44, v193, v34
	v_fma_f32 v34, v19, v0, v42
	v_pk_mul_f32 v[38:39], v[20:21], v[0:1]
	v_and_b32_e32 v42, 0xffff0000, v2
	v_fma_f32 v0, v19, v41, v38
	v_mov_b32_e32 v40, v42
	v_add_f32_e32 v34, v43, v34
	v_add_f32_e32 v0, v39, v0
	v_pk_mul_f32 v[38:39], v[22:23], v[40:41]
	v_lshlrev_b32_e32 v2, 16, v3
	v_add_f32_e32 v45, v193, v34
	v_add_f32_e32 v46, v193, v0
	v_and_b32_e32 v43, 0xffff0000, v3
	v_fma_f32 v0, v19, v1, v39
	v_lshlrev_b32_e32 v3, 16, v35
	v_mov_b32_e32 v34, v2
	v_mov_b32_e32 v35, v42
	v_add_f32_e32 v0, v38, v0
	v_pk_mul_f32 v[34:35], v[18:19], v[34:35]
	v_add_f32_e32 v47, v193, v0
	v_fma_f32 v0, v20, v1, v35
	v_pk_mul_f32 v[38:39], v[20:21], v[42:43]
	v_add_f32_e32 v0, v34, v0
	v_add_f32_e32 v34, v193, v0
	v_fma_f32 v0, v19, v2, v38
	v_add_f32_e32 v0, v39, v0
	v_add_f32_e32 v35, v193, v0
	v_pk_mul_f32 v[24:25], v[24:25], v[2:3]
	ds_read_b128 v[0:3], v33
	ds_read_b128 v[38:41], v33 offset:16
	v_fma_f32 v24, v19, v43, v24
	v_fmac_f32_e32 v24, v18, v25
	s_add_u32 s6, s82, 0x8000
	s_waitcnt lgkmcnt(1)
	v_mul_f32_e32 v0, v0, v37
	v_mul_f32_e32 v1, v1, v44
	v_mul_f32_e32 v2, v2, v45
	v_add_f32_e32 v24, v193, v24
	s_waitcnt lgkmcnt(0)
	v_mul_f32_e32 v25, v38, v47
	v_mul_f32_e32 v33, v39, v34
	v_mul_f32_e32 v3, v3, v46
	v_cvt_pk_bf16_f32 v0, v0, v1
	v_cvt_pk_bf16_f32 v1, v2, v3
	v_cvt_pk_bf16_f32 v2, v25, v33
	s_addc_u32 s7, s83, 0
	v_mul_f32_e32 v34, v40, v35
	v_mul_f32_e32 v24, v41, v24
	v_cvt_pk_bf16_f32 v3, v34, v24
	global_store_dwordx4 v16, v[0:3], s[6:7]
	s_add_i32 s80, s80, s74
	s_cmpk_gt_i32 s80, 0x3ff
	v_lshlrev_b32_e32 v0, 16, v51
	v_and_b32_e32 v2, 0xffff0000, v4
	v_mul_f32_e32 v16, v52, v0
	v_lshlrev_b32_e32 v1, 16, v4
	v_mov_b32_e32 v0, v2
	v_pk_mul_f32 v[24:25], v[18:19], v[0:1]
	v_lshlrev_b32_e32 v4, 16, v5
	v_fma_f32 v0, v20, v16, v25
	v_mov_b32_e32 v34, v4
	v_mov_b32_e32 v35, v2
	v_add_f32_e32 v0, v24, v0
	v_pk_mul_f32 v[34:35], v[18:19], v[34:35]
	v_and_b32_e32 v3, 0xffff0000, v5
	v_add_f32_e32 v16, v193, v0
	v_fma_f32 v0, v20, v1, v35
	v_pk_mul_f32 v[24:25], v[20:21], v[2:3]
	v_add_f32_e32 v0, v34, v0
	v_add_f32_e32 v33, v193, v0
	v_fma_f32 v0, v19, v4, v24
	v_lshlrev_b32_e32 v5, 16, v6
	v_add_f32_e32 v0, v25, v0
	v_add_f32_e32 v34, v193, v0
	v_pk_mul_f32 v[0:1], v[20:21], v[4:5]
	v_and_b32_e32 v24, 0xffff0000, v6
	v_fma_f32 v0, v19, v3, v0
	v_add_f32_e32 v0, v1, v0
	v_mov_b32_e32 v2, v24
	v_add_f32_e32 v35, v193, v0
	v_pk_mul_f32 v[0:1], v[22:23], v[2:3]
	v_lshlrev_b32_e32 v2, 16, v7
	v_and_b32_e32 v25, 0xffff0000, v7
	v_fma_f32 v1, v19, v5, v1
	v_mov_b32_e32 v6, v2
	v_mov_b32_e32 v7, v24
	v_add_f32_e32 v0, v0, v1
	v_pk_mul_f32 v[6:7], v[18:19], v[6:7]
	v_add_f32_e32 v37, v193, v0
	v_pk_mul_f32 v[0:1], v[20:21], v[24:25]
	v_fma_f32 v4, v20, v5, v7
	v_add_f32_e32 v4, v6, v4
	v_fma_f32 v0, v19, v2, v0
	v_lshlrev_b32_e32 v3, 16, v50
	v_add_f32_e32 v24, v193, v4
	v_add_f32_e32 v0, v1, v0
	v_add_u32_e32 v4, s85, v58
	v_add_f32_e32 v38, v193, v0
	v_pk_mul_f32 v[26:27], v[26:27], v[2:3]
	ds_read_b128 v[0:3], v4
	ds_read_b128 v[4:7], v4 offset:16
	v_fma_f32 v25, v19, v25, v26
	v_fmac_f32_e32 v25, v18, v27
	v_add_f32_e32 v25, v193, v25
	s_waitcnt lgkmcnt(1)
; #define LAS __attribute__((address_space(3)))
; __device__ __forceinline__ unsigned pk2(float lo, float hi) { unsigned r; asm("v_cvt_pk_bf16_f32 %0, %1, %2" : "=v"(r) : "v"(lo), "v"(hi)); return r; }
; __device__ __forceinline__ float bflo(unsigned w) { return __uint_as_float(w << 16); }
; __device__ __forceinline__ float bfhi(unsigned w) { return __uint_as_float(w & 0xffff0000u); }
; __device__ __forceinline__ float bf1(bf16 h) { return __uint_as_float((unsigned)h << 16); }
; __device__ __forceinline__ void conv8(const bf16* row, int p0, float c0, float c1, float c2, float cb, float (&o)[8]) {
;     const v4u w = *(const v4u*)(row + p0);
;     float x[10];
;     x[0] = bf1(row[p0 > 0 ? p0 - 1 : 0]) * (p0 > 0 ? 1.f : 0.f); x[9] = bf1(row[p0 + 8 < SEQL ? p0 + 8 : SEQL - 1]) * (p0 + 8 < SEQL ? 1.f : 0.f);
;     x[1] = bflo(w.x); x[2] = bfhi(w.x); x[3] = bflo(w.y); x[4] = bfhi(w.y); x[5] = bflo(w.z); x[6] = bfhi(w.z); x[7] = bflo(w.w); x[8] = bfhi(w.w);
; #pragma unroll
;     for (int e = 0; e < 8; ++e) o[e] = c0 * x[e] + c1 * x[e + 1] + c2 * x[e + 2] + cb;
; }
; template <int VAR> __device__ __forceinline__ void hyena_conv_phase(const Frame& F, const bf16* ZT, const bf16* GT, const float* conv_w, const float* conv_b, const float* skip, float* gscr, float* zscr, bf16* UT) {
;     ...
;         int te = t0; asm volatile("" : "+v"(te));
; #pragma unroll
;         for (int qi = 0; qi < 8; ++qi) { const int q = te + 512 * qi; const int b = qi >> 2, p0 = (q & 2047) * 8; float c0[8];
;             conv8(rx0 + b * SEQL, p0, a0, a1, a2, ab, c0);
;             const f32x4 y0 = *(LAS f32x4*)(X + b * SEQL + p0), y1 = *(LAS f32x4*)(X + b * SEQL + p0 + 4);
;             float u[8];
; #pragma unroll
;             for (int e = 0; e < 4; ++e) { u[e] = y0[e] * c0[e]; u[4 + e] = y1[e] * c0[4 + e]; }
;             v4u o; o.x = pk2(u[0], u[1]); o.y = pk2(u[2], u[3]); o.z = pk2(u[4], u[5]); o.w = pk2(u[6], u[7]);
;             *(v4u*)(UT + (size_t)c * MTOK + b * SEQL + p0) = o; }
;         __syncthreads();
	v_mul_f32_e32 v0, v0, v16
	v_mul_f32_e32 v1, v1, v33
	v_mul_f32_e32 v2, v2, v34
	s_waitcnt lgkmcnt(0)
	v_mul_f32_e32 v4, v4, v37
	v_mul_f32_e32 v5, v5, v24
	v_mul_f32_e32 v3, v3, v35
	v_cvt_pk_bf16_f32 v0, v0, v1
	v_cvt_pk_bf16_f32 v1, v2, v3
	v_cvt_pk_bf16_f32 v2, v4, v5
	v_mul_f32_e32 v6, v6, v38
	v_mul_f32_e32 v7, v7, v25
	v_cvt_pk_bf16_f32 v3, v6, v7
	global_store_dwordx4 v32, v[0:3], s[6:7]
	s_waitcnt vmcnt(3)
	s_nop 1
	v_mov_b32_e32 v8, v82
	v_mov_b32_e32 v9, v83
	v_mov_b32_e32 v10, v84
	v_mov_b32_e32 v11, v85
	v_lshlrev_b32_e32 v7, 16, v10
	v_lshlrev_b32_e32 v0, 16, v57
	v_and_b32_e32 v2, 0xffff0000, v8
	v_mul_f32_e32 v6, v59, v0
	v_lshlrev_b32_e32 v1, 16, v8
	v_mov_b32_e32 v0, v2
	v_pk_mul_f32 v[4:5], v[18:19], v[0:1]
	v_and_b32_e32 v3, 0xffff0000, v9
	v_fma_f32 v0, v20, v6, v5
	v_lshlrev_b32_e32 v6, 16, v9
	v_mov_b32_e32 v8, v6
	v_mov_b32_e32 v9, v2
	v_add_f32_e32 v0, v4, v0
	v_pk_mul_f32 v[8:9], v[18:19], v[8:9]
	v_add_f32_e32 v16, v193, v0
	v_fma_f32 v0, v20, v1, v9
	v_pk_mul_f32 v[4:5], v[20:21], v[2:3]
	v_add_f32_e32 v0, v8, v0
	v_add_f32_e32 v24, v193, v0
	v_fma_f32 v0, v19, v6, v4
	v_add_f32_e32 v0, v5, v0
	v_add_f32_e32 v25, v193, v0
	v_pk_mul_f32 v[0:1], v[20:21], v[6:7]
	v_and_b32_e32 v8, 0xffff0000, v10
	v_fma_f32 v0, v19, v3, v0
	v_add_f32_e32 v0, v1, v0
	v_mov_b32_e32 v2, v8
	v_add_f32_e32 v26, v193, v0
	v_pk_mul_f32 v[0:1], v[22:23], v[2:3]
	v_lshlrev_b32_e32 v2, 16, v11
	v_fma_f32 v1, v19, v7, v1
	v_mov_b32_e32 v4, v2
	v_mov_b32_e32 v5, v8
	v_and_b32_e32 v9, 0xffff0000, v11
	v_add_f32_e32 v0, v0, v1
	v_pk_mul_f32 v[4:5], v[18:19], v[4:5]
	v_add_f32_e32 v27, v193, v0
	v_pk_mul_f32 v[0:1], v[20:21], v[8:9]
	v_fma_f32 v5, v20, v7, v5
	v_add_f32_e32 v4, v4, v5
	v_fma_f32 v0, v19, v2, v0
	v_lshlrev_b32_e32 v3, 16, v56
	v_add_f32_e32 v8, v193, v4
	v_add_f32_e32 v0, v1, v0
	v_add_u32_e32 v4, s85, v68
	v_add_f32_e32 v32, v193, v0
	v_pk_mul_f32 v[10:11], v[28:29], v[2:3]
	ds_read_b128 v[0:3], v4
	ds_read_b128 v[4:7], v4 offset:16
	v_fma_f32 v9, v19, v9, v10
	v_fmac_f32_e32 v9, v18, v11
	v_add_f32_e32 v9, v193, v9
	s_waitcnt lgkmcnt(1)
	v_mul_f32_e32 v0, v0, v16
	v_mul_f32_e32 v1, v1, v24
	v_mul_f32_e32 v2, v2, v25
	s_waitcnt lgkmcnt(0)
	v_mul_f32_e32 v4, v4, v27
	v_mul_f32_e32 v5, v5, v8
	v_mul_f32_e32 v3, v3, v26
	v_cvt_pk_bf16_f32 v0, v0, v1
	v_cvt_pk_bf16_f32 v1, v2, v3
	v_cvt_pk_bf16_f32 v2, v4, v5
	v_mul_f32_e32 v6, v6, v32
	v_mul_f32_e32 v7, v7, v9
	v_cvt_pk_bf16_f32 v3, v6, v7
	global_store_dwordx4 v36, v[0:3], s[6:7]
	s_waitcnt vmcnt(0)
	s_nop 1
	v_mov_b32_e32 v55, v104
	v_mov_b32_e32 v61, v106
	v_mov_b32_e32 v12, v134
	v_mov_b32_e32 v13, v135
	v_mov_b32_e32 v14, v136
	v_mov_b32_e32 v15, v137
	v_lshlrev_b32_e32 v7, 16, v14
	v_lshlrev_b32_e32 v0, 16, v61
	v_and_b32_e32 v2, 0xffff0000, v12
	v_mul_f32_e32 v6, v54, v0
	v_lshlrev_b32_e32 v1, 16, v12
	v_mov_b32_e32 v0, v2
	v_pk_mul_f32 v[4:5], v[18:19], v[0:1]
	v_mov_b32_e32 v9, v2
	v_fma_f32 v0, v20, v6, v5
	v_lshlrev_b32_e32 v6, 16, v13
	v_mov_b32_e32 v8, v6
	v_add_f32_e32 v0, v4, v0
	v_pk_mul_f32 v[8:9], v[18:19], v[8:9]
	v_and_b32_e32 v3, 0xffff0000, v13
	v_add_f32_e32 v12, v193, v0
	v_fma_f32 v0, v20, v1, v9
	v_pk_mul_f32 v[4:5], v[20:21], v[2:3]
	v_add_f32_e32 v0, v8, v0
	v_add_f32_e32 v13, v193, v0
	v_fma_f32 v0, v19, v6, v4
	v_add_f32_e32 v0, v5, v0
	v_add_f32_e32 v16, v193, v0
	v_pk_mul_f32 v[0:1], v[20:21], v[6:7]
	v_and_b32_e32 v8, 0xffff0000, v14
	v_fma_f32 v0, v19, v3, v0
	v_add_f32_e32 v0, v1, v0
	v_mov_b32_e32 v2, v8
	v_add_f32_e32 v24, v193, v0
	v_pk_mul_f32 v[0:1], v[22:23], v[2:3]
	v_lshlrev_b32_e32 v2, 16, v15
	v_fma_f32 v1, v19, v7, v1
	v_mov_b32_e32 v4, v2
	v_mov_b32_e32 v5, v8
	v_and_b32_e32 v9, 0xffff0000, v15
	v_add_f32_e32 v0, v0, v1
	v_pk_mul_f32 v[4:5], v[18:19], v[4:5]
	v_add_f32_e32 v14, v193, v0
	v_pk_mul_f32 v[0:1], v[20:21], v[8:9]
	v_fma_f32 v5, v20, v7, v5
	v_add_f32_e32 v4, v4, v5
	v_fma_f32 v0, v19, v2, v0
	v_lshlrev_b32_e32 v3, 16, v55
	v_add_f32_e32 v8, v193, v4
	v_add_f32_e32 v0, v1, v0
	v_add_u32_e32 v4, s85, v53
	v_add_f32_e32 v15, v193, v0
	v_pk_mul_f32 v[10:11], v[30:31], v[2:3]
	ds_read_b128 v[0:3], v4
	ds_read_b128 v[4:7], v4 offset:16
	v_fma_f32 v9, v19, v9, v10
	v_fmac_f32_e32 v9, v18, v11
	v_add_f32_e32 v9, v193, v9
	s_waitcnt lgkmcnt(1)
	v_mul_f32_e32 v0, v0, v12
	v_mul_f32_e32 v1, v1, v13
	v_mul_f32_e32 v2, v2, v16
	v_mul_f32_e32 v3, v3, v24
	s_waitcnt lgkmcnt(0)
	v_mul_f32_e32 v4, v4, v14
	v_mul_f32_e32 v5, v5, v8
	v_mul_f32_e32 v6, v6, v15
	v_mul_f32_e32 v7, v7, v9
	v_cvt_pk_bf16_f32 v0, v0, v1
	v_cvt_pk_bf16_f32 v1, v2, v3
	v_cvt_pk_bf16_f32 v2, v4, v5
	v_cvt_pk_bf16_f32 v3, v6, v7
	global_store_dwordx4 v60, v[0:3], s[6:7]
	s_barrier
	s_cbranch_scc1 .LBB0_347
; #define LAS __attribute__((address_space(3)))
; __device__ __forceinline__ float bflo(unsigned w) { return __uint_as_float(w << 16); }
; __device__ __forceinline__ float bfhi(unsigned w) { return __uint_as_float(w & 0xffff0000u); }
; __device__ __forceinline__ void conv8(const bf16* row, int p0, float c0, float c1, float c2, float cb, float (&o)[8]) {
;     const v4u w = *(const v4u*)(row + p0);
;     float x[10];
;     x[0] = bf1(row[p0 > 0 ? p0 - 1 : 0]) * (p0 > 0 ? 1.f : 0.f); x[9] = bf1(row[p0 + 8 < SEQL ? p0 + 8 : SEQL - 1]) * (p0 + 8 < SEQL ? 1.f : 0.f);
;     x[1] = bflo(w.x); x[2] = bfhi(w.x); x[3] = bflo(w.y); x[4] = bfhi(w.y); x[5] = bflo(w.z); x[6] = bfhi(w.z); x[7] = bflo(w.w); x[8] = bfhi(w.w);
; #pragma unroll
;     for (int e = 0; e < 8; ++e) o[e] = c0 * x[e] + c1 * x[e + 1] + c2 * x[e + 2] + cb;
; }
; template <int VAR> __device__ __forceinline__ void hyena_conv_phase(const Frame& F, const bf16* ZT, const bf16* GT, const float* conv_w, const float* conv_b, const float* skip, float* gscr, float* zscr, bf16* UT) {
;     ...
;     for (int c = F.bid; c < DM; c += F.G) {
;         const bf16* rx0 = ZT + (size_t)c * MTOK; const bf16* rx1 = ZT + (size_t)(DM + c) * MTOK; const bf16* rv = ZT + (size_t)(2 * DM + c) * MTOK;
;         const float a0 = conv_w[c], a1 = conv_w[3072 + c], a2 = conv_w[6144 + c], ab = conv_b[c];
;         const float b0 = conv_w[DM + c], b1 = conv_w[3072 + DM + c], b2 = conv_w[6144 + DM + c], bb = conv_b[DM + c];
;         const float v0 = conv_w[2 * DM + c], v1 = conv_w[3072 + 2 * DM + c], v2 = conv_w[6144 + 2 * DM + c], vb = conv_b[2 * DM + c];
;         const bf16* gf = GT + (size_t)c * SEQL; const bf16* gb = GT + (size_t)(DM + c) * SEQL;
;         int t = t0; asm volatile("" : "+v"(t));
;         float gsc = 1.f; const float skn = skip[c] * (1.0f / 32768.0f);
; #pragma unroll
;         for (int qi = 0; qi < 8; ++qi) { const int q = t + 512 * qi; const int b = qi >> 2, p0 = (q & 2047) * 8; float cv[8], cx[8];
;             conv8(rv + b * SEQL, p0, v0, v1, v2, vb, cv); conv8(rx1 + b * SEQL, p0, b0, b1, b2, bb, cx);
;             f32x4 o0, o1;
; #pragma unroll
;             for (int e = 0; e < 4; ++e) { o0[e] = cv[e] * cx[e]; o1[e] = cv[4 + e] * cx[4 + e]; }
;             *(LAS f32x4*)(X + b * SEQL + p0) = o0; *(LAS f32x4*)(X + b * SEQL + p0 + 4) = o1; }
.LBB0_323:
	s_add_i32 s6, s80, 0x400
	s_ashr_i32 s81, s80, 31
	s_ashr_i32 s7, s6, 31
	s_lshl_b64 s[82:83], s[80:81], 15
	s_lshl_b64 s[20:21], s[6:7], 16
	s_add_u32 s90, s40, s20
	s_addc_u32 s91, s41, s21
	s_lshl_b64 s[20:21], s[80:81], 16
	s_add_u32 s10, s40, s20
	s_addc_u32 s20, s41, s21
	s_add_u32 s92, s10, 0x8000000
	s_addc_u32 s93, s20, 0
	s_lshl_b64 s[76:77], s[80:81], 2
	s_add_u32 s88, s48, s76
	s_addc_u32 s89, s49, s77
	s_add_u32 s94, s50, s76
	s_addc_u32 s95, s51, s77
	global_load_dword v19, v152, s[88:89]
	global_load_dword v18, v153, s[88:89]
	global_load_dword v24, v154, s[88:89]
	global_load_dword v16, v154, s[94:95]
	global_load_dword v20, v17, s[88:89]
	global_load_dword v193, v17, s[94:95]
	global_load_dword v31, v158, s[88:89]
	global_load_dword v28, v159, s[88:89]
	global_load_dword v25, v155, s[88:89]
	global_load_dword v26, v156, s[88:89]
	global_load_dword v30, v157, s[88:89]
	global_load_dword v32, v157, s[94:95]
	s_lshl_b64 s[88:89], s[6:7], 15
	v_mov_b32_e32 v22, v221
	s_add_u32 s6, s14, s76
	v_lshlrev_b32_e32 v27, 3, v22
	s_addc_u32 s7, s15, s77
	v_and_b32_e32 v29, 0x3ff8, v27
	v_lshlrev_b32_e32 v23, 1, v29
	s_add_u32 s94, s10, 0x8008000
	v_sub_u32_e64 v8, v29, 1 clamp
	global_load_dwordx4 v[0:3], v23, s[92:93]
	global_load_dwordx4 v[4:7], v23, s[90:91]
	s_addc_u32 s95, s20, 0
	v_lshlrev_b32_e32 v8, 1, v8
	v_min_u32_e32 v9, 0x3ff7, v29
	s_add_u32 s96, s90, 0x8000
	v_lshlrev_b32_e32 v9, 1, v9
	s_addc_u32 s97, s91, 0
	global_load_ushort v47, v8, s[92:93]
	global_load_ushort v49, v9, s[92:93] offset:16
	global_load_ushort v37, v8, s[94:95]
	global_load_ushort v33, v8, s[96:97]
	global_load_ushort v39, v9, s[94:95] offset:16
	global_load_ushort v38, v9, s[96:97] offset:16
	global_load_ushort v52, v9, s[90:91] offset:16
	global_load_ushort v56, v8, s[90:91]
	global_load_dword v21, v17, s[6:7]
	v_add_u32_e32 v8, 0x1000, v27
	v_and_b32_e32 v78, 0x3ff8, v8
	v_lshlrev_b32_e32 v35, 1, v78
	v_sub_u32_e64 v8, v78, 1 clamp
	v_min_u32_e32 v9, 0x3ff7, v78
	v_lshlrev_b32_e32 v34, 1, v8
	v_lshlrev_b32_e32 v36, 1, v9
	global_load_dwordx4 v[12:15], v35, s[92:93]
	global_load_dwordx4 v[8:11], v35, s[90:91]
	global_load_ushort v68, v34, s[92:93]
	global_load_ushort v69, v36, s[92:93] offset:16
	global_load_ushort v42, v36, s[94:95] offset:16
	global_load_ushort v43, v36, s[96:97] offset:16
	global_load_ushort v70, v36, s[90:91] offset:16
	global_load_ushort v45, v34, s[94:95]
	global_load_ushort v44, v34, s[96:97]
	global_load_ushort v71, v34, s[90:91]
	v_bitop3_b32 v218, v27, s87, v160 bitop3:0x6c
	v_sub_u32_e64 v219, v218, 1 clamp
	v_lshlrev_b32_e32 v230, 1, v219
	global_load_ushort v86, v230, s[92:93]
	v_bitop3_b32 v218, v27, s87, v160 bitop3:0x6c
	v_lshlrev_b32_e32 v219, 1, v218
	global_load_dwordx4 v[134:137], v219, s[92:93]
	v_bitop3_b32 v218, v27, s87, v160 bitop3:0x6c
	v_min_u32_e32 v219, 0x3ff7, v218
	v_lshlrev_b32_e32 v230, 1, v219
	global_load_ushort v88, v230, s[92:93] offset:16
	v_bitop3_b32 v218, v27, s87, v160 bitop3:0x6c
	v_min_u32_e32 v219, 0x3ff7, v218
	v_lshlrev_b32_e32 v230, 1, v219
	global_load_ushort v90, v230, s[94:95] offset:16
	v_bitop3_b32 v218, v27, s87, v160 bitop3:0x6c
	v_min_u32_e32 v219, 0x3ff7, v218
	v_lshlrev_b32_e32 v230, 1, v219
	global_load_ushort v92, v230, s[96:97] offset:16
	v_bitop3_b32 v218, v27, s87, v160 bitop3:0x6c
	v_min_u32_e32 v219, 0x3ff7, v218
	v_lshlrev_b32_e32 v230, 1, v219
	global_load_ushort v94, v230, s[90:91] offset:16
	v_bitop3_b32 v218, v27, s87, v160 bitop3:0x6c
	v_sub_u32_e64 v219, v218, 1 clamp
	v_lshlrev_b32_e32 v230, 1, v219
	global_load_ushort v96, v230, s[94:95]
	v_bitop3_b32 v218, v27, s87, v160 bitop3:0x6c
	v_sub_u32_e64 v219, v218, 1 clamp
	v_lshlrev_b32_e32 v230, 1, v219
	global_load_ushort v98, v230, s[96:97]
	v_bitop3_b32 v218, v27, s87, v160 bitop3:0x6c
	v_sub_u32_e64 v219, v218, 1 clamp
	v_lshlrev_b32_e32 v230, 1, v219
	global_load_ushort v100, v230, s[90:91]
	v_bitop3_b32 v218, v27, s87, v160 bitop3:0x6c
	v_lshlrev_b32_e32 v219, 1, v218
	global_load_dwordx4 v[138:141], v219, s[90:91]
	v_add_u32_e32 v218, 0x3000, v27
	v_and_b32_e32 v219, 0x3ff8, v218
	v_sub_u32_e64 v230, v219, 1 clamp
	v_lshlrev_b32_e32 v232, 1, v230
	global_load_ushort v102, v232, s[92:93]
	v_add_u32_e32 v218, 0x3000, v27
	v_and_b32_e32 v219, 0x3ff8, v218
	v_lshlrev_b32_e32 v230, 1, v219
	global_load_dwordx4 v[142:145], v230, s[92:93]
	v_add_u32_e32 v218, 0x3000, v27
	v_and_b32_e32 v219, 0x3ff8, v218
	v_min_u32_e32 v230, 0x3ff7, v219
	v_lshlrev_b32_e32 v232, 1, v230
	global_load_ushort v104, v232, s[92:93] offset:16
	v_add_u32_e32 v218, 0x3000, v27
	v_and_b32_e32 v219, 0x3ff8, v218
	v_min_u32_e32 v230, 0x3ff7, v219
	v_lshlrev_b32_e32 v232, 1, v230
	global_load_ushort v106, v232, s[94:95] offset:16
	v_add_u32_e32 v218, 0x3000, v27
	v_and_b32_e32 v219, 0x3ff8, v218
	v_min_u32_e32 v230, 0x3ff7, v219
	v_lshlrev_b32_e32 v232, 1, v230
	global_load_ushort v108, v232, s[96:97] offset:16
	v_add_u32_e32 v218, 0x3000, v27
	v_and_b32_e32 v219, 0x3ff8, v218
	v_min_u32_e32 v230, 0x3ff7, v219
	v_lshlrev_b32_e32 v232, 1, v230
	global_load_ushort v110, v232, s[90:91] offset:16
	v_add_u32_e32 v218, 0x3000, v27
	v_and_b32_e32 v219, 0x3ff8, v218
	v_sub_u32_e64 v230, v219, 1 clamp
	v_lshlrev_b32_e32 v232, 1, v230
	global_load_ushort v112, v232, s[94:95]
	v_add_u32_e32 v218, 0x3000, v27
	v_and_b32_e32 v219, 0x3ff8, v218
	v_sub_u32_e64 v230, v219, 1 clamp
	v_lshlrev_b32_e32 v232, 1, v230
	global_load_ushort v114, v232, s[96:97]
	v_add_u32_e32 v218, 0x3000, v27
	v_and_b32_e32 v219, 0x3ff8, v218
	v_sub_u32_e64 v230, v219, 1 clamp
	v_lshlrev_b32_e32 v232, 1, v230
	global_load_ushort v116, v232, s[90:91]
	v_add_u32_e32 v218, 0x3000, v27
	v_and_b32_e32 v219, 0x3ff8, v218
	v_lshlrev_b32_e32 v230, 1, v219
	global_load_dwordx4 v[146:149], v230, s[90:91]
	global_load_dwordx4 v[212:215], v23, s[94:95]
	global_load_dwordx4 v[222:225], v23, s[96:97]
	global_load_dwordx4 v[226:229], v35, s[94:95]
	global_load_dwordx4 v[236:239], v35, s[96:97]
	v_bitop3_b32 v218, v27, s87, v160 bitop3:0x6c
	v_lshlrev_b32_e32 v219, 1, v218
	global_load_dwordx4 v[240:243], v219, s[94:95]
	v_bitop3_b32 v218, v27, s87, v160 bitop3:0x6c
	v_lshlrev_b32_e32 v219, 1, v218
	global_load_dwordx4 v[244:247], v219, s[96:97]
	v_add_u32_e32 v218, 0x3000, v27
	v_and_b32_e32 v219, 0x3ff8, v218
	v_lshlrev_b32_e32 v230, 1, v219
	global_load_dwordx4 v[250:253], v230, s[94:95]
	v_cmp_eq_u32_e32 vcc, 0, v29
	v_bitop3_b32 v79, v27, s87, v160 bitop3:0x6c
	s_add_u32 s88, s16, s88
	v_cndmask_b32_e64 v40, 1.0, 0, vcc
	v_cmp_eq_u32_e32 vcc, s11, v29
	s_addc_u32 s89, s17, s89
	v_mov_b32_e32 v210, 1.0
	v_cndmask_b32_e64 v41, 1.0, 0, vcc
	v_cmp_eq_u32_e32 vcc, 0, v78
	s_mov_b32 s81, 0
	s_waitcnt vmcnt(47)
; #define LAS __attribute__((address_space(3)))
; __device__ __forceinline__ float bflo(unsigned w) { return __uint_as_float(w << 16); }
; __device__ __forceinline__ float bfhi(unsigned w) { return __uint_as_float(w & 0xffff0000u); }
; __device__ __forceinline__ float bf1(bf16 h) { return __uint_as_float((unsigned)h << 16); }
; __device__ __forceinline__ void conv8(const bf16* row, int p0, float c0, float c1, float c2, float cb, float (&o)[8]) {
;     const v4u w = *(const v4u*)(row + p0);
;     float x[10];
;     x[0] = bf1(row[p0 > 0 ? p0 - 1 : 0]) * (p0 > 0 ? 1.f : 0.f); x[9] = bf1(row[p0 + 8 < SEQL ? p0 + 8 : SEQL - 1]) * (p0 + 8 < SEQL ? 1.f : 0.f);
;     x[1] = bflo(w.x); x[2] = bfhi(w.x); x[3] = bflo(w.y); x[4] = bfhi(w.y); x[5] = bflo(w.z); x[6] = bfhi(w.z); x[7] = bflo(w.w); x[8] = bfhi(w.w);
; #pragma unroll
;     for (int e = 0; e < 8; ++e) o[e] = c0 * x[e] + c1 * x[e + 1] + c2 * x[e + 2] + cb;
; }
; template <int VAR> __device__ __forceinline__ void hyena_conv_phase(const Frame& F, const bf16* ZT, const bf16* GT, const float* conv_w, const float* conv_b, const float* skip, float* gscr, float* zscr, bf16* UT) {
;     ...
; #pragma unroll
;         for (int qi = 0; qi < 8; ++qi) { const int q = t + 512 * qi; const int b = qi >> 2, p0 = (q & 2047) * 8; float cv[8], cx[8];
;             conv8(rv + b * SEQL, p0, v0, v1, v2, vb, cv); conv8(rx1 + b * SEQL, p0, b0, b1, b2, bb, cx);
;             f32x4 o0, o1;
; #pragma unroll
;             for (int e = 0; e < 4; ++e) { o0[e] = cv[e] * cx[e]; o1[e] = cv[4 + e] * cx[4 + e]; }
;             *(LAS f32x4*)(X + b * SEQL + p0) = o0; *(LAS f32x4*)(X + b * SEQL + p0 + 4) = o1; }
	v_lshlrev_b32_e32 v34, 16, v0
	v_and_b32_e32 v51, s0, v1
	v_and_b32_e32 v50, 0xffff0000, v0
	v_lshlrev_b32_e32 v53, 16, v1
	s_waitcnt vmcnt(46)
	v_and_b32_e32 v55, s0, v5
	v_and_b32_e32 v54, 0xffff0000, v4
	v_lshlrev_b32_e32 v57, 16, v5
	s_waitcnt vmcnt(45)
	v_lshlrev_b32_e32 v0, 16, v47
	s_waitcnt vmcnt(39)
	v_pk_mov_b32 v[50:51], v[52:53], v[50:51] op_sel:[1,0]
	s_waitcnt vmcnt(38)
	v_pk_mov_b32 v[54:55], v[56:57], v[54:55] op_sel:[1,0]
	v_mul_f32_e32 v58, v40, v0
	v_lshlrev_b32_e32 v0, 16, v56
	v_mov_b32_e32 v59, v51
	v_mov_b32_e32 v61, v55
	v_mul_f32_e32 v60, v40, v0
	v_lshlrev_b32_e32 v36, 16, v4
	v_pk_mul_f32 v[58:59], v[30:31], v[58:59]
	v_pk_mul_f32 v[60:61], v[24:25], v[60:61]
	v_pk_fma_f32 v[58:59], v[30:31], v[34:35], v[58:59] op_sel:[0,0,1] op_sel_hi:[1,0,0]
	v_pk_fma_f32 v[60:61], v[24:25], v[36:37], v[60:61] op_sel:[0,0,1] op_sel_hi:[1,0,0]
	v_pk_fma_f32 v[58:59], v[28:29], v[50:51], v[58:59] op_sel_hi:[0,1,1]
	v_pk_fma_f32 v[60:61], v[26:27], v[54:55], v[60:61] op_sel_hi:[0,1,1]
	v_lshlrev_b32_e32 v4, 16, v49
	v_pk_add_f32 v[58:59], v[32:33], v[58:59] op_sel_hi:[0,1]
	v_pk_add_f32 v[60:61], v[16:17], v[60:61] op_sel_hi:[0,1]
	v_and_b32_e32 v46, 0xffff0000, v3
	v_mul_f32_e32 v47, v41, v4
	v_lshlrev_b32_e32 v4, 16, v52
	v_pk_mul_f32 v[58:59], v[58:59], v[60:61]
	v_and_b32_e32 v61, 16, v2
	v_and_b32_e32 v60, 0xffff0000, v1
	v_lshlrev_b32_e32 v1, 16, v2
	v_and_b32_e32 v63, 16, v3
	v_and_b32_e32 v62, 0xffff0000, v2
	v_lshlrev_b32_e32 v65, 16, v3
	v_and_b32_e32 v3, 16, v6
	v_and_b32_e32 v2, 0xffff0000, v5
	v_mul_f32_e32 v49, v41, v4
	v_mov_b32_e32 v34, v31
	v_mov_b32_e32 v4, v2
	v_mov_b32_e32 v36, v25
	v_pk_mul_f32 v[50:51], v[30:31], v[50:51] op_sel_hi:[0,1]
	v_pk_mul_f32 v[54:55], v[24:25], v[54:55] op_sel_hi:[0,1]
	v_pk_mov_b32 v[52:53], v[52:53], v[60:61] op_sel:[1,0]
	v_pk_mov_b32 v[2:3], v[56:57], v[2:3] op_sel:[1,0]
	v_mov_b32_e32 v0, v60
	v_lshlrev_b32_e32 v5, 16, v6
	v_pk_fma_f32 v[50:51], v[34:35], v[52:53], v[50:51] op_sel:[0,0,1] op_sel_hi:[0,1,0]
	v_pk_fma_f32 v[2:3], v[36:37], v[2:3], v[54:55] op_sel:[0,0,1] op_sel_hi:[0,1,0]
	v_pk_fma_f32 v[50:51], v[28:29], v[0:1], v[50:51] op_sel_hi:[0,1,1]
	v_pk_fma_f32 v[2:3], v[26:27], v[4:5], v[2:3] op_sel_hi:[0,1,1]
	v_pk_add_f32 v[50:51], v[32:33], v[50:51] op_sel_hi:[0,1]
	v_pk_add_f32 v[2:3], v[16:17], v[2:3] op_sel_hi:[0,1]
	v_pk_mul_f32 v[2:3], v[50:51], v[2:3]
	v_mov_b32_e32 v50, v65
	v_mov_b32_e32 v51, v46
	v_and_b32_e32 v48, 0xffff0000, v7
	v_mov_b32_e32 v64, v62
	v_and_b32_e32 v67, 16, v7
	v_and_b32_e32 v66, 0xffff0000, v6
	v_lshlrev_b32_e32 v7, 16, v7
	v_pk_mul_f32 v[50:51], v[34:35], v[50:51] op_sel_hi:[0,1]
	v_pk_mov_b32 v[62:63], v[0:1], v[62:63] op_sel:[1,0]
	v_mov_b32_e32 v6, v66
	v_pk_mov_b32 v[66:67], v[4:5], v[66:67] op_sel:[1,0]
	v_mov_b32_e32 v52, v7
	v_mov_b32_e32 v53, v48
	v_pk_fma_f32 v[50:51], v[30:31], v[64:65], v[50:51] op_sel_hi:[0,1,1]
	v_pk_mul_f32 v[54:55], v[34:35], v[62:63] op_sel_hi:[0,1]
	v_pk_fma_f32 v[46:47], v[28:29], v[46:47], v[50:51] op_sel_hi:[0,1,1]
	v_pk_mul_f32 v[50:51], v[36:37], v[66:67] op_sel_hi:[0,1]
	v_pk_mul_f32 v[52:53], v[36:37], v[52:53] op_sel_hi:[0,1]
	v_pk_fma_f32 v[0:1], v[30:31], v[0:1], v[54:55] op_sel_hi:[0,1,1]
	v_pk_fma_f32 v[52:53], v[24:25], v[6:7], v[52:53] op_sel_hi:[0,1,1]
	v_pk_fma_f32 v[4:5], v[24:25], v[4:5], v[50:51] op_sel_hi:[0,1,1]
	v_pk_fma_f32 v[0:1], v[28:29], v[64:65], v[0:1] op_sel_hi:[0,1,1]
	v_pk_fma_f32 v[4:5], v[26:27], v[6:7], v[4:5] op_sel_hi:[0,1,1]
	v_pk_fma_f32 v[6:7], v[26:27], v[48:49], v[52:53] op_sel_hi:[0,1,1]
	v_pk_add_f32 v[46:47], v[32:33], v[46:47] op_sel_hi:[0,1]
	v_pk_add_f32 v[0:1], v[32:33], v[0:1] op_sel_hi:[0,1]
	v_pk_add_f32 v[6:7], v[16:17], v[6:7] op_sel_hi:[0,1]
	v_pk_add_f32 v[4:5], v[16:17], v[4:5] op_sel_hi:[0,1]
	v_lshlrev_b32_e32 v48, 2, v29
	v_pk_mul_f32 v[4:5], v[0:1], v[4:5]
	v_pk_mul_f32 v[6:7], v[46:47], v[6:7]
	v_add_u32_e32 v46, 0, v48
	v_mov_b32_e32 v0, v59
	v_mov_b32_e32 v1, v58
	ds_write_b128 v46, v[0:3]
	ds_write_b128 v46, v[4:7] offset:16
	v_cndmask_b32_e64 v46, 1.0, 0, vcc
	v_cmp_eq_u32_e32 vcc, s11, v78
	s_waitcnt vmcnt(33)
	v_lshlrev_b32_e32 v1, 16, v69
	v_and_b32_e32 v5, s0, v13
	v_cndmask_b32_e64 v47, 1.0, 0, vcc
	v_mul_f32_e32 v55, v47, v1
	s_waitcnt vmcnt(27)
	v_lshlrev_b32_e32 v1, 16, v71
	v_and_b32_e32 v4, 0xffff0000, v12
	v_lshlrev_b32_e32 v53, 16, v13
	v_lshlrev_b32_e32 v0, 16, v68
	v_mul_f32_e32 v56, v46, v1
	v_lshlrev_b32_e32 v1, 16, v70
	v_pk_mov_b32 v[62:63], v[52:53], v[4:5] op_sel:[1,0]
	v_mul_f32_e32 v0, v46, v0
	v_mul_f32_e32 v59, v47, v1
	v_mov_b32_e32 v1, v63
	v_lshlrev_b32_e32 v2, 16, v12
	v_pk_mul_f32 v[0:1], v[30:31], v[0:1]
	v_min_u32_e32 v7, 0x3ff7, v79
	v_pk_fma_f32 v[0:1], v[30:31], v[2:3], v[0:1] op_sel:[0,0,1] op_sel_hi:[1,0,0]
	v_lshlrev_b32_e32 v7, 1, v7
	v_pk_fma_f32 v[4:5], v[28:29], v[62:63], v[0:1] op_sel_hi:[0,1,1]
	v_sub_u32_e64 v0, v79, 1 clamp
	v_lshlrev_b32_e32 v6, 1, v0
	v_lshlrev_b32_e32 v12, 1, v79
	s_nop 0
	s_nop 0
	s_nop 0
	s_nop 0
	s_nop 0
	s_nop 0
	s_nop 0
	s_nop 0
	s_nop 0
	v_lshlrev_b32_e32 v60, 16, v8
	v_and_b32_e32 v67, s0, v9
	v_and_b32_e32 v66, 0xffff0000, v8
	v_lshlrev_b32_e32 v61, 16, v9
	v_pk_mov_b32 v[66:67], v[60:61], v[66:67] op_sel:[1,0]
	v_pk_add_f32 v[64:65], v[32:33], v[4:5] op_sel_hi:[0,1]
	v_mov_b32_e32 v57, v67
	v_pk_mul_f32 v[56:57], v[24:25], v[56:57]
	v_and_b32_e32 v58, 0xffff0000, v11
	v_pk_fma_f32 v[56:57], v[24:25], v[60:61], v[56:57] op_sel:[0,0,1] op_sel_hi:[1,0,0]
	v_and_b32_e32 v73, 16, v10
	v_pk_fma_f32 v[56:57], v[26:27], v[66:67], v[56:57] op_sel_hi:[0,1,1]
	v_pk_add_f32 v[56:57], v[16:17], v[56:57] op_sel_hi:[0,1]
	v_pk_mul_f32 v[64:65], v[64:65], v[56:57]
	v_and_b32_e32 v57, 16, v14
	v_and_b32_e32 v56, 0xffff0000, v13
	v_mov_b32_e32 v68, v56
	v_and_b32_e32 v72, 0xffff0000, v9
	v_lshlrev_b32_e32 v9, 16, v10
	v_and_b32_e32 v75, 16, v11
	v_and_b32_e32 v74, 0xffff0000, v10
	v_lshlrev_b32_e32 v77, 16, v11
	v_pk_mul_f32 v[10:11], v[30:31], v[62:63] op_sel_hi:[0,1]
	v_pk_mul_f32 v[62:63], v[24:25], v[66:67] op_sel_hi:[0,1]
	v_lshlrev_b32_e32 v69, 16, v14
	v_mov_b32_e32 v8, v72
	s_nop 0
	v_and_b32_e32 v54, 0xffff0000, v15
	v_and_b32_e32 v71, 16, v15
	v_lshlrev_b32_e32 v15, 16, v15
	v_and_b32_e32 v70, 0xffff0000, v14
	v_mov_b32_e32 v14, v70
	v_pk_mov_b32 v[70:71], v[68:69], v[70:71] op_sel:[1,0]
	v_mov_b32_e32 v76, v74
	v_pk_mov_b32 v[74:75], v[8:9], v[74:75] op_sel:[1,0]
	v_cmp_eq_u32_e32 vcc, s87, v29
	v_lshlrev_b32_e32 v79, 2, v79
	v_mul_f32_e32 v21, 0x38000000, v21
	s_waitcnt vmcnt(20)
; #define LAS __attribute__((address_space(3)))
; __device__ __forceinline__ float bflo(unsigned w) { return __uint_as_float(w << 16); }
; __device__ __forceinline__ float bfhi(unsigned w) { return __uint_as_float(w & 0xffff0000u); }
; __device__ __forceinline__ float bf1(bf16 h) { return __uint_as_float((unsigned)h << 16); }
; __device__ __forceinline__ void conv8(const bf16* row, int p0, float c0, float c1, float c2, float cb, float (&o)[8]) {
;     const v4u w = *(const v4u*)(row + p0);
;     float x[10];
;     x[0] = bf1(row[p0 > 0 ? p0 - 1 : 0]) * (p0 > 0 ? 1.f : 0.f); x[9] = bf1(row[p0 + 8 < SEQL ? p0 + 8 : SEQL - 1]) * (p0 + 8 < SEQL ? 1.f : 0.f);
;     x[1] = bflo(w.x); x[2] = bfhi(w.x); x[3] = bflo(w.y); x[4] = bfhi(w.y); x[5] = bflo(w.z); x[6] = bfhi(w.z); x[7] = bflo(w.w); x[8] = bfhi(w.w);
; #pragma unroll
;     for (int e = 0; e < 8; ++e) o[e] = c0 * x[e] + c1 * x[e + 1] + c2 * x[e + 2] + cb;
; }
; template <int VAR> __device__ __forceinline__ void hyena_conv_phase(const Frame& F, const bf16* ZT, const bf16* GT, const float* conv_w, const float* conv_b, const float* skip, float* gscr, float* zscr, bf16* UT) {
;     ...
; #pragma unroll
;         for (int qi = 0; qi < 8; ++qi) { const int q = t + 512 * qi; const int b = qi >> 2, p0 = (q & 2047) * 8; float cv[8], cx[8];
;             conv8(rv + b * SEQL, p0, v0, v1, v2, vb, cv); conv8(rx1 + b * SEQL, p0, b0, b1, b2, bb, cx);
;             f32x4 o0, o1;
; #pragma unroll
;             for (int e = 0; e < 4; ++e) { o0[e] = cv[e] * cx[e]; o1[e] = cv[4 + e] * cx[4 + e]; }
;             *(LAS f32x4*)(X + b * SEQL + p0) = o0; *(LAS f32x4*)(X + b * SEQL + p0 + 4) = o1; }
	s_nop 1
	v_mov_b32_e32 v80, v86
	v_mov_b32_e32 v0, v134
	v_mov_b32_e32 v1, v135
	v_mov_b32_e32 v2, v136
	v_mov_b32_e32 v3, v137
	v_mov_b32_e32 v81, v88
	v_mov_b32_e32 v49, v90
	v_mov_b32_e32 v50, v92
	v_mov_b32_e32 v82, v94
	v_mov_b32_e32 v52, v96
	v_pk_mov_b32 v[56:57], v[52:53], v[56:57] op_sel:[1,0]
	s_nop 0
	v_pk_fma_f32 v[10:11], v[34:35], v[56:57], v[10:11] op_sel:[0,0,1] op_sel_hi:[0,1,0]
	v_pk_mov_b32 v[56:57], v[60:61], v[72:73] op_sel:[1,0]
	v_pk_fma_f32 v[10:11], v[28:29], v[68:69], v[10:11] op_sel_hi:[0,1,1]
	v_pk_fma_f32 v[56:57], v[36:37], v[56:57], v[62:63] op_sel:[0,0,1] op_sel_hi:[0,1,0]
	v_pk_fma_f32 v[56:57], v[26:27], v[8:9], v[56:57] op_sel_hi:[0,1,1]
	v_pk_add_f32 v[10:11], v[32:33], v[10:11] op_sel_hi:[0,1]
	v_pk_add_f32 v[56:57], v[16:17], v[56:57] op_sel_hi:[0,1]
	v_pk_mul_f32 v[10:11], v[10:11], v[56:57]
	v_mov_b32_e32 v56, v15
	v_mov_b32_e32 v57, v54
	v_pk_mul_f32 v[56:57], v[34:35], v[56:57] op_sel_hi:[0,1]
	v_pk_fma_f32 v[56:57], v[30:31], v[14:15], v[56:57] op_sel_hi:[0,1,1]
	v_pk_fma_f32 v[54:55], v[28:29], v[54:55], v[56:57] op_sel_hi:[0,1,1]
	v_mov_b32_e32 v60, v77
	v_mov_b32_e32 v61, v58
	v_pk_mul_f32 v[62:63], v[34:35], v[70:71] op_sel_hi:[0,1]
	v_pk_add_f32 v[56:57], v[32:33], v[54:55] op_sel_hi:[0,1]
	v_pk_mul_f32 v[54:55], v[36:37], v[74:75] op_sel_hi:[0,1]
	v_pk_fma_f32 v[62:63], v[30:31], v[68:69], v[62:63] op_sel_hi:[0,1,1]
	v_pk_mul_f32 v[60:61], v[36:37], v[60:61] op_sel_hi:[0,1]
	v_pk_fma_f32 v[8:9], v[24:25], v[8:9], v[54:55] op_sel_hi:[0,1,1]
	v_pk_fma_f32 v[14:15], v[28:29], v[14:15], v[62:63] op_sel_hi:[0,1,1]
	v_pk_fma_f32 v[60:61], v[24:25], v[76:77], v[60:61] op_sel_hi:[0,1,1]
	v_pk_fma_f32 v[8:9], v[26:27], v[76:77], v[8:9] op_sel_hi:[0,1,1]
	v_pk_add_f32 v[14:15], v[32:33], v[14:15] op_sel_hi:[0,1]
	v_pk_fma_f32 v[54:55], v[26:27], v[58:59], v[60:61] op_sel_hi:[0,1,1]
	v_pk_add_f32 v[8:9], v[16:17], v[8:9] op_sel_hi:[0,1]
	v_lshlrev_b32_e32 v53, 2, v78
	v_pk_add_f32 v[58:59], v[16:17], v[54:55] op_sel_hi:[0,1]
	v_pk_mul_f32 v[54:55], v[14:15], v[8:9]
	v_add_u32_e32 v13, 0, v53
	v_mov_b32_e32 v8, v65
	v_mov_b32_e32 v9, v64
	v_pk_mul_f32 v[56:57], v[56:57], v[58:59]
	ds_write_b128 v13, v[8:11]
	ds_write_b128 v13, v[54:57] offset:16
	v_lshlrev_b32_e32 v9, 16, v80
	v_cndmask_b32_e64 v8, 1.0, 0, vcc
	v_cmp_eq_u32_e32 vcc, s33, v29
	v_mul_f32_e32 v10, v8, v9
	v_lshlrev_b32_e32 v11, 16, v81
	v_cndmask_b32_e64 v9, 1.0, 0, vcc
	v_mul_f32_e32 v15, v9, v11
	s_waitcnt vmcnt(18)
	s_nop 1
	v_mov_b32_e32 v51, v98
	v_mov_b32_e32 v83, v100
	v_lshlrev_b32_e32 v11, 16, v83
	v_and_b32_e32 v57, s0, v1
	v_and_b32_e32 v56, 0xffff0000, v0
	v_lshlrev_b32_e32 v13, 16, v1
	v_mul_f32_e32 v62, v8, v11
	v_lshlrev_b32_e32 v11, 16, v82
	v_pk_mov_b32 v[68:69], v[12:13], v[56:57] op_sel:[1,0]
	v_mul_f32_e32 v65, v9, v11
	v_mov_b32_e32 v11, v69
	v_lshlrev_b32_e32 v54, 16, v0
	v_pk_mul_f32 v[10:11], v[30:31], v[10:11]
	v_add_u32_e32 v0, 0x3000, v27
	v_pk_fma_f32 v[10:11], v[30:31], v[54:55], v[10:11] op_sel:[0,0,1] op_sel_hi:[1,0,0]
	s_waitcnt vmcnt(17)
	s_nop 1
	v_mov_b32_e32 v4, v138
	v_mov_b32_e32 v5, v139
	v_mov_b32_e32 v6, v140
	v_mov_b32_e32 v7, v141
	v_and_b32_e32 v71, s0, v5
	v_pk_fma_f32 v[10:11], v[28:29], v[68:69], v[10:11] op_sel_hi:[0,1,1]
	v_and_b32_e32 v29, 0x3ff8, v0
	v_sub_u32_e64 v0, v29, 1 clamp
	v_lshlrev_b32_e32 v0, 1, v0
	v_min_u32_e32 v27, 0x3ff7, v29
	v_lshlrev_b32_e32 v76, 1, v29
	s_nop 0
	s_nop 0
	v_lshlrev_b32_e32 v27, 1, v27
	s_nop 0
	s_nop 0
	s_nop 0
	s_nop 0
	s_nop 0
	s_nop 0
	s_nop 0
	v_and_b32_e32 v70, 0xffff0000, v4
	v_lshlrev_b32_e32 v27, 16, v5
	v_pk_mov_b32 v[70:71], v[26:27], v[70:71] op_sel:[1,0]
	s_nop 0
	v_mov_b32_e32 v63, v71
	v_lshlrev_b32_e32 v66, 16, v4
	v_pk_mul_f32 v[62:63], v[24:25], v[62:63]
	v_pk_add_f32 v[10:11], v[32:33], v[10:11] op_sel_hi:[0,1]
	v_pk_fma_f32 v[62:63], v[24:25], v[66:67], v[62:63] op_sel:[0,0,1] op_sel_hi:[1,0,0]
	v_and_b32_e32 v14, 0xffff0000, v3
	v_pk_fma_f32 v[62:63], v[26:27], v[70:71], v[62:63] op_sel_hi:[0,1,1]
	v_pk_add_f32 v[62:63], v[16:17], v[62:63] op_sel_hi:[0,1]
	v_pk_mul_f32 v[10:11], v[10:11], v[62:63]
	v_and_b32_e32 v63, 16, v2
	v_and_b32_e32 v62, 0xffff0000, v1
	v_lshlrev_b32_e32 v1, 16, v2
	v_and_b32_e32 v67, 16, v3
	v_and_b32_e32 v66, 0xffff0000, v2
	v_lshlrev_b32_e32 v73, 16, v3
	v_and_b32_e32 v3, 16, v6
	v_and_b32_e32 v2, 0xffff0000, v5
	v_mov_b32_e32 v0, v62
	v_mov_b32_e32 v4, v2
	v_pk_mul_f32 v[68:69], v[30:31], v[68:69] op_sel_hi:[0,1]
	v_pk_mul_f32 v[70:71], v[24:25], v[70:71] op_sel_hi:[0,1]
	v_pk_mov_b32 v[62:63], v[12:13], v[62:63] op_sel:[1,0]
	v_pk_mov_b32 v[2:3], v[26:27], v[2:3] op_sel:[1,0]
	v_lshlrev_b32_e32 v5, 16, v6
	v_pk_fma_f32 v[62:63], v[34:35], v[62:63], v[68:69] op_sel:[0,0,1] op_sel_hi:[0,1,0]
	v_pk_fma_f32 v[2:3], v[36:37], v[2:3], v[70:71] op_sel:[0,0,1] op_sel_hi:[0,1,0]
	v_pk_fma_f32 v[62:63], v[28:29], v[0:1], v[62:63] op_sel_hi:[0,1,1]
	v_pk_fma_f32 v[2:3], v[26:27], v[4:5], v[2:3] op_sel_hi:[0,1,1]
	v_pk_add_f32 v[62:63], v[32:33], v[62:63] op_sel_hi:[0,1]
	v_pk_add_f32 v[2:3], v[16:17], v[2:3] op_sel_hi:[0,1]
	v_pk_mul_f32 v[2:3], v[62:63], v[2:3]
	v_mov_b32_e32 v62, v73
	v_mov_b32_e32 v63, v14
	v_mov_b32_e32 v72, v66
	v_and_b32_e32 v75, 16, v7
	v_and_b32_e32 v74, 0xffff0000, v6
	v_pk_mul_f32 v[62:63], v[34:35], v[62:63] op_sel_hi:[0,1]
	v_and_b32_e32 v64, 0xffff0000, v7
	v_pk_mov_b32 v[66:67], v[0:1], v[66:67] op_sel:[1,0]
	v_lshlrev_b32_e32 v7, 16, v7
	v_mov_b32_e32 v6, v74
	v_pk_mov_b32 v[74:75], v[4:5], v[74:75] op_sel:[1,0]
	v_pk_fma_f32 v[62:63], v[30:31], v[72:73], v[62:63] op_sel_hi:[0,1,1]
	v_mov_b32_e32 v68, v7
	v_mov_b32_e32 v69, v64
	v_pk_mul_f32 v[66:67], v[34:35], v[66:67] op_sel_hi:[0,1]
	v_pk_fma_f32 v[14:15], v[28:29], v[14:15], v[62:63] op_sel_hi:[0,1,1]
	v_pk_mul_f32 v[62:63], v[36:37], v[74:75] op_sel_hi:[0,1]
	v_pk_fma_f32 v[0:1], v[30:31], v[0:1], v[66:67] op_sel_hi:[0,1,1]
	v_pk_mul_f32 v[66:67], v[36:37], v[68:69] op_sel_hi:[0,1]
	v_pk_fma_f32 v[4:5], v[24:25], v[4:5], v[62:63] op_sel_hi:[0,1,1]
	v_pk_fma_f32 v[0:1], v[28:29], v[72:73], v[0:1] op_sel_hi:[0,1,1]
	v_pk_fma_f32 v[66:67], v[24:25], v[6:7], v[66:67] op_sel_hi:[0,1,1]
	v_pk_fma_f32 v[4:5], v[26:27], v[6:7], v[4:5] op_sel_hi:[0,1,1]
	v_pk_add_f32 v[0:1], v[32:33], v[0:1] op_sel_hi:[0,1]
	v_pk_fma_f32 v[6:7], v[26:27], v[64:65], v[66:67] op_sel_hi:[0,1,1]
	v_pk_add_f32 v[4:5], v[16:17], v[4:5] op_sel_hi:[0,1]
	v_pk_add_f32 v[14:15], v[32:33], v[14:15] op_sel_hi:[0,1]
	v_pk_add_f32 v[6:7], v[16:17], v[6:7] op_sel_hi:[0,1]
	v_pk_mul_f32 v[4:5], v[0:1], v[4:5]
	v_add_u32_e32 v13, 0, v79
	v_mov_b32_e32 v0, v11
	v_mov_b32_e32 v1, v10
	v_cmp_eq_u32_e32 vcc, 0, v29
	v_pk_mul_f32 v[6:7], v[14:15], v[6:7]
	ds_write_b128 v13, v[0:3]
	ds_write_b128 v13, v[4:7] offset:16
	s_add_u32 s90, s16, s82
	s_addc_u32 s91, s17, s83
	s_waitcnt vmcnt(16)
; #define LAS __attribute__((address_space(3)))
; __device__ __forceinline__ float bflo(unsigned w) { return __uint_as_float(w << 16); }
; __device__ __forceinline__ float bfhi(unsigned w) { return __uint_as_float(w & 0xffff0000u); }
; __device__ __forceinline__ float bf1(bf16 h) { return __uint_as_float((unsigned)h << 16); }
; __device__ __forceinline__ void conv8(const bf16* row, int p0, float c0, float c1, float c2, float cb, float (&o)[8]) {
;     const v4u w = *(const v4u*)(row + p0);
;     float x[10];
;     x[0] = bf1(row[p0 > 0 ? p0 - 1 : 0]) * (p0 > 0 ? 1.f : 0.f); x[9] = bf1(row[p0 + 8 < SEQL ? p0 + 8 : SEQL - 1]) * (p0 + 8 < SEQL ? 1.f : 0.f);
;     x[1] = bflo(w.x); x[2] = bfhi(w.x); x[3] = bflo(w.y); x[4] = bfhi(w.y); x[5] = bflo(w.z); x[6] = bfhi(w.z); x[7] = bflo(w.w); x[8] = bfhi(w.w);
; #pragma unroll
;     for (int e = 0; e < 8; ++e) o[e] = c0 * x[e] + c1 * x[e + 1] + c2 * x[e + 2] + cb;
; }
; template <int VAR> __device__ __forceinline__ void hyena_conv_phase(const Frame& F, const bf16* ZT, const bf16* GT, const float* conv_w, const float* conv_b, const float* skip, float* gscr, float* zscr, bf16* UT) {
;     ...
; #pragma unroll
;         for (int qi = 0; qi < 8; ++qi) { const int q = t + 512 * qi; const int b = qi >> 2, p0 = (q & 2047) * 8; float cv[8], cx[8];
;             conv8(rv + b * SEQL, p0, v0, v1, v2, vb, cv); conv8(rx1 + b * SEQL, p0, b0, b1, b2, bb, cx);
;             f32x4 o0, o1;
; #pragma unroll
;             for (int e = 0; e < 4; ++e) { o0[e] = cv[e] * cx[e]; o1[e] = cv[4 + e] * cx[4 + e]; }
;             *(LAS f32x4*)(X + b * SEQL + p0) = o0; *(LAS f32x4*)(X + b * SEQL + p0 + 4) = o1; }
	s_nop 1
	v_mov_b32_e32 v77, v102
	v_lshlrev_b32_e32 v0, 16, v77
	v_cndmask_b32_e64 v77, 1.0, 0, vcc
	v_cmp_eq_u32_e32 vcc, s11, v29
	v_mul_f32_e32 v4, v77, v0
	s_waitcnt vmcnt(14)
	s_nop 1
	v_mov_b32_e32 v54, v142
	v_mov_b32_e32 v55, v143
	v_mov_b32_e32 v56, v144
	v_mov_b32_e32 v57, v145
	v_mov_b32_e32 v78, v104
	v_lshlrev_b32_e32 v0, 16, v78
	v_cndmask_b32_e64 v78, 1.0, 0, vcc
	v_mul_f32_e32 v11, v78, v0
	s_waitcnt vmcnt(8)
	s_nop 1
	v_mov_b32_e32 v80, v106
	v_mov_b32_e32 v81, v108
	v_mov_b32_e32 v82, v110
	v_mov_b32_e32 v83, v112
	v_mov_b32_e32 v84, v114
	v_mov_b32_e32 v85, v116
	v_lshlrev_b32_e32 v0, 16, v85
	v_mul_f32_e32 v14, v77, v0
	v_lshlrev_b32_e32 v0, 16, v82
	v_mul_f32_e32 v63, v78, v0
	v_and_b32_e32 v67, s0, v55
	v_and_b32_e32 v66, 0xffff0000, v54
	s_nop 0
	v_lshlrev_b32_e32 v13, 16, v55
	v_pk_mov_b32 v[66:67], v[12:13], v[66:67] op_sel:[1,0]
	v_lshlrev_b32_e32 v6, 16, v54
	v_mov_b32_e32 v5, v67
	v_pk_mul_f32 v[4:5], v[30:31], v[4:5]
	s_waitcnt vmcnt(7)
	s_nop 1
	v_mov_b32_e32 v58, v146
	v_mov_b32_e32 v59, v147
	v_mov_b32_e32 v60, v148
	v_mov_b32_e32 v61, v149
	v_and_b32_e32 v71, s0, v59
	v_pk_fma_f32 v[68:69], v[30:31], v[6:7], v[4:5] op_sel:[0,0,1] op_sel_hi:[1,0,0]
	s_nop 0
	v_and_b32_e32 v70, 0xffff0000, v58
	v_lshlrev_b32_e32 v23, 16, v59
	v_pk_mov_b32 v[70:71], v[22:23], v[70:71] op_sel:[1,0]
	v_lshlrev_b32_e32 v64, 16, v58
	v_mov_b32_e32 v15, v71
	v_pk_mul_f32 v[14:15], v[24:25], v[14:15]
	v_pk_fma_f32 v[68:69], v[28:29], v[66:67], v[68:69] op_sel_hi:[0,1,1]
	v_pk_fma_f32 v[14:15], v[24:25], v[64:65], v[14:15] op_sel:[0,0,1] op_sel_hi:[1,0,0]
	v_pk_add_f32 v[68:69], v[32:33], v[68:69] op_sel_hi:[0,1]
	v_pk_fma_f32 v[14:15], v[26:27], v[70:71], v[14:15] op_sel_hi:[0,1,1]
	v_pk_add_f32 v[14:15], v[16:17], v[14:15] op_sel_hi:[0,1]
	v_and_b32_e32 v10, 0xffff0000, v57
	v_pk_mul_f32 v[14:15], v[68:69], v[14:15]
	v_and_b32_e32 v65, 16, v56
	v_and_b32_e32 v64, 0xffff0000, v55
	v_lshlrev_b32_e32 v55, 16, v56
	v_and_b32_e32 v69, 16, v57
	v_and_b32_e32 v68, 0xffff0000, v56
	v_lshlrev_b32_e32 v73, 16, v57
	v_and_b32_e32 v57, 16, v60
	v_and_b32_e32 v56, 0xffff0000, v59
	v_mov_b32_e32 v54, v64
	v_mov_b32_e32 v58, v56
	v_pk_mul_f32 v[66:67], v[30:31], v[66:67] op_sel_hi:[0,1]
	v_pk_mul_f32 v[70:71], v[24:25], v[70:71] op_sel_hi:[0,1]
	v_pk_mov_b32 v[64:65], v[12:13], v[64:65] op_sel:[1,0]
	v_pk_mov_b32 v[56:57], v[22:23], v[56:57] op_sel:[1,0]
	v_lshlrev_b32_e32 v59, 16, v60
	v_pk_fma_f32 v[64:65], v[34:35], v[64:65], v[66:67] op_sel:[0,0,1] op_sel_hi:[0,1,0]
	v_pk_fma_f32 v[56:57], v[36:37], v[56:57], v[70:71] op_sel:[0,0,1] op_sel_hi:[0,1,0]
	v_pk_fma_f32 v[64:65], v[28:29], v[54:55], v[64:65] op_sel_hi:[0,1,1]
	v_pk_fma_f32 v[56:57], v[26:27], v[58:59], v[56:57] op_sel_hi:[0,1,1]
	v_pk_add_f32 v[64:65], v[32:33], v[64:65] op_sel_hi:[0,1]
	v_pk_add_f32 v[56:57], v[16:17], v[56:57] op_sel_hi:[0,1]
	v_pk_mul_f32 v[56:57], v[64:65], v[56:57]
	v_mov_b32_e32 v64, v73
	v_mov_b32_e32 v65, v10
	v_and_b32_e32 v62, 0xffff0000, v61
	v_mov_b32_e32 v72, v68
	v_and_b32_e32 v75, 16, v61
	v_and_b32_e32 v74, 0xffff0000, v60
	v_lshlrev_b32_e32 v61, 16, v61
	v_pk_mul_f32 v[64:65], v[34:35], v[64:65] op_sel_hi:[0,1]
	v_mov_b32_e32 v60, v74
	v_pk_mov_b32 v[74:75], v[58:59], v[74:75] op_sel:[1,0]
	v_mov_b32_e32 v66, v61
	v_mov_b32_e32 v67, v62
	v_pk_fma_f32 v[64:65], v[30:31], v[72:73], v[64:65] op_sel_hi:[0,1,1]
	v_pk_mov_b32 v[68:69], v[54:55], v[68:69] op_sel:[1,0]
	v_pk_fma_f32 v[10:11], v[28:29], v[10:11], v[64:65] op_sel_hi:[0,1,1]
	v_pk_mul_f32 v[64:65], v[36:37], v[74:75] op_sel_hi:[0,1]
	v_pk_mul_f32 v[66:67], v[36:37], v[66:67] op_sel_hi:[0,1]
	v_pk_mul_f32 v[68:69], v[34:35], v[68:69] op_sel_hi:[0,1]
	v_pk_fma_f32 v[66:67], v[24:25], v[60:61], v[66:67] op_sel_hi:[0,1,1]
	v_pk_fma_f32 v[58:59], v[24:25], v[58:59], v[64:65] op_sel_hi:[0,1,1]
	v_pk_fma_f32 v[54:55], v[30:31], v[54:55], v[68:69] op_sel_hi:[0,1,1]
	v_pk_fma_f32 v[58:59], v[26:27], v[60:61], v[58:59] op_sel_hi:[0,1,1]
	v_pk_fma_f32 v[60:61], v[26:27], v[62:63], v[66:67] op_sel_hi:[0,1,1]
	v_pk_fma_f32 v[54:55], v[28:29], v[72:73], v[54:55] op_sel_hi:[0,1,1]
	v_pk_add_f32 v[10:11], v[32:33], v[10:11] op_sel_hi:[0,1]
	v_pk_add_f32 v[60:61], v[16:17], v[60:61] op_sel_hi:[0,1]
	v_pk_add_f32 v[54:55], v[32:33], v[54:55] op_sel_hi:[0,1]
	v_pk_add_f32 v[58:59], v[16:17], v[58:59] op_sel_hi:[0,1]
	v_pk_mul_f32 v[60:61], v[10:11], v[60:61]
	v_lshlrev_b32_e32 v29, 2, v29
	v_lshlrev_b32_e32 v11, 16, v39
	v_pk_mul_f32 v[58:59], v[54:55], v[58:59]
	v_add_u32_e32 v10, 0, v29
	v_mov_b32_e32 v54, v15
	v_mov_b32_e32 v55, v14
	v_mul_f32_e32 v15, v41, v11
	v_lshlrev_b32_e32 v11, 16, v33
	ds_write_b128 v10, v[54:57]
	ds_write_b128 v10, v[58:61] offset:16
	v_lshlrev_b32_e32 v10, 16, v37
	v_mul_f32_e32 v60, v40, v11
	v_lshlrev_b32_e32 v11, 16, v38
	v_mul_f32_e32 v10, v40, v10
	v_mul_f32_e32 v63, v41, v11
	s_waitcnt vmcnt(6)
	s_nop 1
	v_mov_b32_e32 v0, v212
	v_mov_b32_e32 v1, v213
	v_mov_b32_e32 v2, v214
	v_mov_b32_e32 v3, v215
	v_and_b32_e32 v55, s0, v1
	s_nop 0
	v_and_b32_e32 v54, 0xffff0000, v0
	v_lshlrev_b32_e32 v13, 16, v1
	v_pk_mov_b32 v[66:67], v[12:13], v[54:55] op_sel:[1,0]
	v_lshlrev_b32_e32 v58, 16, v0
	v_mov_b32_e32 v11, v67
	v_pk_mul_f32 v[10:11], v[30:31], v[10:11]
	s_nop 0
	v_pk_fma_f32 v[10:11], v[30:31], v[58:59], v[10:11] op_sel:[0,0,1] op_sel_hi:[1,0,0]
	s_waitcnt vmcnt(5)
; #define LAS __attribute__((address_space(3)))
; __device__ __forceinline__ float bflo(unsigned w) { return __uint_as_float(w << 16); }
; __device__ __forceinline__ float bfhi(unsigned w) { return __uint_as_float(w & 0xffff0000u); }
; __device__ __forceinline__ float bf1(bf16 h) { return __uint_as_float((unsigned)h << 16); }
; __device__ __forceinline__ void conv8(const bf16* row, int p0, float c0, float c1, float c2, float cb, float (&o)[8]) {
;     const v4u w = *(const v4u*)(row + p0);
;     float x[10];
;     x[0] = bf1(row[p0 > 0 ? p0 - 1 : 0]) * (p0 > 0 ? 1.f : 0.f); x[9] = bf1(row[p0 + 8 < SEQL ? p0 + 8 : SEQL - 1]) * (p0 + 8 < SEQL ? 1.f : 0.f);
;     x[1] = bflo(w.x); x[2] = bfhi(w.x); x[3] = bflo(w.y); x[4] = bfhi(w.y); x[5] = bflo(w.z); x[6] = bfhi(w.z); x[7] = bflo(w.w); x[8] = bfhi(w.w);
; #pragma unroll
;     for (int e = 0; e < 8; ++e) o[e] = c0 * x[e] + c1 * x[e + 1] + c2 * x[e + 2] + cb;
; }
; template <int VAR> __device__ __forceinline__ void hyena_conv_phase(const Frame& F, const bf16* ZT, const bf16* GT, const float* conv_w, const float* conv_b, const float* skip, float* gscr, float* zscr, bf16* UT) {
;     ...
; #pragma unroll
;         for (int qi = 0; qi < 8; ++qi) { const int q = t + 512 * qi; const int b = qi >> 2, p0 = (q & 2047) * 8; float cv[8], cx[8];
;             conv8(rv + b * SEQL, p0, v0, v1, v2, vb, cv); conv8(rx1 + b * SEQL, p0, b0, b1, b2, bb, cx);
;             f32x4 o0, o1;
; #pragma unroll
;             for (int e = 0; e < 4; ++e) { o0[e] = cv[e] * cx[e]; o1[e] = cv[4 + e] * cx[4 + e]; }
;             *(LAS f32x4*)(X + b * SEQL + p0) = o0; *(LAS f32x4*)(X + b * SEQL + p0 + 4) = o1; }
	s_nop 1
	v_mov_b32_e32 v4, v222
	v_mov_b32_e32 v5, v223
	v_mov_b32_e32 v6, v224
	v_mov_b32_e32 v7, v225
	v_and_b32_e32 v59, s0, v5
	v_and_b32_e32 v58, 0xffff0000, v4
	v_lshlrev_b32_e32 v23, 16, v5
	v_pk_mov_b32 v[58:59], v[22:23], v[58:59] op_sel:[1,0]
	v_lshlrev_b32_e32 v64, 16, v4
	v_mov_b32_e32 v61, v59
	v_pk_mul_f32 v[60:61], v[24:25], v[60:61]
	v_pk_fma_f32 v[10:11], v[28:29], v[66:67], v[10:11] op_sel_hi:[0,1,1]
	v_pk_fma_f32 v[60:61], v[24:25], v[64:65], v[60:61] op_sel:[0,0,1] op_sel_hi:[1,0,0]
	v_pk_add_f32 v[10:11], v[32:33], v[10:11] op_sel_hi:[0,1]
	v_pk_fma_f32 v[60:61], v[26:27], v[58:59], v[60:61] op_sel_hi:[0,1,1]
	v_pk_add_f32 v[60:61], v[16:17], v[60:61] op_sel_hi:[0,1]
	v_and_b32_e32 v14, 0xffff0000, v3
	v_pk_mul_f32 v[10:11], v[10:11], v[60:61]
	v_and_b32_e32 v61, 16, v2
	v_and_b32_e32 v60, 0xffff0000, v1
	v_lshlrev_b32_e32 v1, 16, v2
	v_and_b32_e32 v65, 16, v3
	v_and_b32_e32 v64, 0xffff0000, v2
	v_lshlrev_b32_e32 v69, 16, v3
	v_and_b32_e32 v3, 16, v6
	v_and_b32_e32 v2, 0xffff0000, v5
	v_mov_b32_e32 v0, v60
	v_mov_b32_e32 v4, v2
	v_pk_mul_f32 v[66:67], v[30:31], v[66:67] op_sel_hi:[0,1]
	v_pk_mul_f32 v[58:59], v[24:25], v[58:59] op_sel_hi:[0,1]
	v_pk_mov_b32 v[60:61], v[12:13], v[60:61] op_sel:[1,0]
	v_pk_mov_b32 v[2:3], v[22:23], v[2:3] op_sel:[1,0]
	v_lshlrev_b32_e32 v5, 16, v6
	v_pk_fma_f32 v[60:61], v[34:35], v[60:61], v[66:67] op_sel:[0,0,1] op_sel_hi:[0,1,0]
	v_pk_fma_f32 v[2:3], v[36:37], v[2:3], v[58:59] op_sel:[0,0,1] op_sel_hi:[0,1,0]
	v_mov_b32_e32 v58, v69
	v_mov_b32_e32 v59, v14
	v_mov_b32_e32 v68, v64
	v_and_b32_e32 v71, 16, v7
	v_and_b32_e32 v70, 0xffff0000, v6
	v_pk_fma_f32 v[60:61], v[28:29], v[0:1], v[60:61] op_sel_hi:[0,1,1]
	v_pk_fma_f32 v[2:3], v[26:27], v[4:5], v[2:3] op_sel_hi:[0,1,1]
	v_pk_mul_f32 v[58:59], v[34:35], v[58:59] op_sel_hi:[0,1]
	v_and_b32_e32 v62, 0xffff0000, v7
	v_pk_mov_b32 v[64:65], v[0:1], v[64:65] op_sel:[1,0]
	v_lshlrev_b32_e32 v7, 16, v7
	v_mov_b32_e32 v6, v70
	v_pk_mov_b32 v[70:71], v[4:5], v[70:71] op_sel:[1,0]
	v_pk_add_f32 v[60:61], v[32:33], v[60:61] op_sel_hi:[0,1]
	v_pk_add_f32 v[2:3], v[16:17], v[2:3] op_sel_hi:[0,1]
	v_pk_fma_f32 v[58:59], v[30:31], v[68:69], v[58:59] op_sel_hi:[0,1,1]
	v_pk_mul_f32 v[2:3], v[60:61], v[2:3]
	v_mov_b32_e32 v60, v7
	v_mov_b32_e32 v61, v62
	v_pk_mul_f32 v[64:65], v[34:35], v[64:65] op_sel_hi:[0,1]
	v_pk_fma_f32 v[14:15], v[28:29], v[14:15], v[58:59] op_sel_hi:[0,1,1]
	v_pk_mul_f32 v[58:59], v[36:37], v[70:71] op_sel_hi:[0,1]
	v_pk_fma_f32 v[0:1], v[30:31], v[0:1], v[64:65] op_sel_hi:[0,1,1]
	v_pk_mul_f32 v[60:61], v[36:37], v[60:61] op_sel_hi:[0,1]
	v_pk_fma_f32 v[4:5], v[24:25], v[4:5], v[58:59] op_sel_hi:[0,1,1]
	v_pk_fma_f32 v[0:1], v[28:29], v[68:69], v[0:1] op_sel_hi:[0,1,1]
	v_pk_fma_f32 v[60:61], v[24:25], v[6:7], v[60:61] op_sel_hi:[0,1,1]
	v_pk_fma_f32 v[4:5], v[26:27], v[6:7], v[4:5] op_sel_hi:[0,1,1]
	v_pk_add_f32 v[0:1], v[32:33], v[0:1] op_sel_hi:[0,1]
	v_pk_fma_f32 v[6:7], v[26:27], v[62:63], v[60:61] op_sel_hi:[0,1,1]
	v_pk_add_f32 v[4:5], v[16:17], v[4:5] op_sel_hi:[0,1]
	v_pk_add_f32 v[14:15], v[32:33], v[14:15] op_sel_hi:[0,1]
	v_pk_add_f32 v[6:7], v[16:17], v[6:7] op_sel_hi:[0,1]
	v_pk_mul_f32 v[4:5], v[0:1], v[4:5]
	v_add_u32_e32 v13, s85, v48
	v_mov_b32_e32 v0, v11
	v_mov_b32_e32 v1, v10
	v_pk_mul_f32 v[6:7], v[14:15], v[6:7]
	ds_write_b128 v13, v[0:3]
	ds_write_b128 v13, v[4:7] offset:16
	v_lshlrev_b32_e32 v0, 16, v45
	v_mul_f32_e32 v4, v46, v0
	v_lshlrev_b32_e32 v0, 16, v42
	v_mul_f32_e32 v11, v47, v0
	v_lshlrev_b32_e32 v0, 16, v44
	v_mul_f32_e32 v42, v46, v0
	v_lshlrev_b32_e32 v0, 16, v43
	v_mul_f32_e32 v45, v47, v0
	s_nop 0
	s_waitcnt vmcnt(4)
	s_nop 1
	v_mov_b32_e32 v38, v226
	v_mov_b32_e32 v39, v227
	v_mov_b32_e32 v40, v228
	v_mov_b32_e32 v41, v229
	v_and_b32_e32 v7, s0, v39
	v_and_b32_e32 v6, 0xffff0000, v38
	v_lshlrev_b32_e32 v13, 16, v39
	v_pk_mov_b32 v[58:59], v[12:13], v[6:7] op_sel:[1,0]
	v_lshlrev_b32_e32 v14, 16, v38
	v_mov_b32_e32 v5, v59
	v_pk_mul_f32 v[60:61], v[30:31], v[4:5]
	s_waitcnt vmcnt(3)
	s_nop 1
	v_mov_b32_e32 v54, v236
	v_mov_b32_e32 v55, v237
	v_mov_b32_e32 v56, v238
	v_mov_b32_e32 v57, v239
	v_lshlrev_b32_e32 v23, 16, v55
	v_pk_fma_f32 v[14:15], v[30:31], v[14:15], v[60:61] op_sel:[0,0,1] op_sel_hi:[1,0,0]
	v_and_b32_e32 v61, s0, v55
	v_and_b32_e32 v60, 0xffff0000, v54
	v_pk_mov_b32 v[60:61], v[22:23], v[60:61] op_sel:[1,0]
	v_lshlrev_b32_e32 v46, 16, v54
	v_mov_b32_e32 v43, v61
	s_nop 0
	v_pk_mul_f32 v[42:43], v[24:25], v[42:43]
	v_pk_fma_f32 v[14:15], v[28:29], v[58:59], v[14:15] op_sel_hi:[0,1,1]
	v_pk_fma_f32 v[42:43], v[24:25], v[46:47], v[42:43] op_sel:[0,0,1] op_sel_hi:[1,0,0]
	v_pk_add_f32 v[14:15], v[32:33], v[14:15] op_sel_hi:[0,1]
	v_pk_fma_f32 v[42:43], v[26:27], v[60:61], v[42:43] op_sel_hi:[0,1,1]
	v_pk_add_f32 v[42:43], v[16:17], v[42:43] op_sel_hi:[0,1]
	v_pk_mul_f32 v[14:15], v[14:15], v[42:43]
	v_and_b32_e32 v43, 16, v40
	v_and_b32_e32 v42, 0xffff0000, v39
	v_and_b32_e32 v63, 16, v56
	v_and_b32_e32 v62, 0xffff0000, v55
	v_mov_b32_e32 v38, v42
	v_pk_mul_f32 v[58:59], v[30:31], v[58:59] op_sel_hi:[0,1]
	v_pk_mul_f32 v[60:61], v[24:25], v[60:61] op_sel_hi:[0,1]
	v_pk_mov_b32 v[12:13], v[12:13], v[42:43] op_sel:[1,0]
	v_pk_mov_b32 v[42:43], v[22:23], v[62:63] op_sel:[1,0]
	v_lshlrev_b32_e32 v39, 16, v40
	v_lshlrev_b32_e32 v55, 16, v56
	v_mov_b32_e32 v54, v62
	v_pk_fma_f32 v[12:13], v[34:35], v[12:13], v[58:59] op_sel:[0,0,1] op_sel_hi:[0,1,0]
	v_pk_fma_f32 v[42:43], v[36:37], v[42:43], v[60:61] op_sel:[0,0,1] op_sel_hi:[0,1,0]
	v_pk_fma_f32 v[12:13], v[28:29], v[38:39], v[12:13] op_sel_hi:[0,1,1]
	v_pk_fma_f32 v[42:43], v[26:27], v[54:55], v[42:43] op_sel_hi:[0,1,1]
; #define LAS __attribute__((address_space(3)))
; __device__ __forceinline__ float bflo(unsigned w) { return __uint_as_float(w << 16); }
; __device__ __forceinline__ float bfhi(unsigned w) { return __uint_as_float(w & 0xffff0000u); }
; __device__ __forceinline__ float bf1(bf16 h) { return __uint_as_float((unsigned)h << 16); }
; __device__ __forceinline__ void conv8(const bf16* row, int p0, float c0, float c1, float c2, float cb, float (&o)[8]) {
;     const v4u w = *(const v4u*)(row + p0);
;     float x[10];
;     x[0] = bf1(row[p0 > 0 ? p0 - 1 : 0]) * (p0 > 0 ? 1.f : 0.f); x[9] = bf1(row[p0 + 8 < SEQL ? p0 + 8 : SEQL - 1]) * (p0 + 8 < SEQL ? 1.f : 0.f);
;     x[1] = bflo(w.x); x[2] = bfhi(w.x); x[3] = bflo(w.y); x[4] = bfhi(w.y); x[5] = bflo(w.z); x[6] = bfhi(w.z); x[7] = bflo(w.w); x[8] = bfhi(w.w);
; #pragma unroll
;     for (int e = 0; e < 8; ++e) o[e] = c0 * x[e] + c1 * x[e + 1] + c2 * x[e + 2] + cb;
; }
; template <int VAR> __device__ __forceinline__ void hyena_conv_phase(const Frame& F, const bf16* ZT, const bf16* GT, const float* conv_w, const float* conv_b, const float* skip, float* gscr, float* zscr, bf16* UT) {
;     ...
;         for (int qi = 0; qi < 8; ++qi) { const int q = t + 512 * qi; const int b = qi >> 2, p0 = (q & 2047) * 8; float cv[8], cx[8];
;             conv8(rv + b * SEQL, p0, v0, v1, v2, vb, cv); conv8(rx1 + b * SEQL, p0, b0, b1, b2, bb, cx);
;             f32x4 o0, o1;
; #pragma unroll
;             for (int e = 0; e < 4; ++e) { o0[e] = cv[e] * cx[e]; o1[e] = cv[4 + e] * cx[4 + e]; }
;             *(LAS f32x4*)(X + b * SEQL + p0) = o0; *(LAS f32x4*)(X + b * SEQL + p0 + 4) = o1; }
	v_and_b32_e32 v10, 0xffff0000, v41
	v_and_b32_e32 v47, 16, v41
	v_and_b32_e32 v46, 0xffff0000, v40
	v_lshlrev_b32_e32 v41, 16, v41
	v_pk_add_f32 v[12:13], v[32:33], v[12:13] op_sel_hi:[0,1]
	v_pk_add_f32 v[42:43], v[16:17], v[42:43] op_sel_hi:[0,1]
	v_mov_b32_e32 v40, v46
	v_pk_mov_b32 v[46:47], v[38:39], v[46:47] op_sel:[1,0]
	v_pk_mul_f32 v[12:13], v[12:13], v[42:43]
	v_mov_b32_e32 v42, v41
	v_mov_b32_e32 v43, v10
	v_and_b32_e32 v44, 0xffff0000, v57
	v_and_b32_e32 v65, 16, v57
	v_and_b32_e32 v64, 0xffff0000, v56
	v_lshlrev_b32_e32 v57, 16, v57
	v_pk_mul_f32 v[46:47], v[34:35], v[46:47] op_sel_hi:[0,1]
	v_pk_mul_f32 v[42:43], v[34:35], v[42:43] op_sel_hi:[0,1]
	v_mov_b32_e32 v56, v64
	v_pk_mov_b32 v[64:65], v[54:55], v[64:65] op_sel:[1,0]
	v_mov_b32_e32 v58, v57
	v_mov_b32_e32 v59, v44
	v_pk_fma_f32 v[42:43], v[30:31], v[40:41], v[42:43] op_sel_hi:[0,1,1]
	v_pk_fma_f32 v[38:39], v[30:31], v[38:39], v[46:47] op_sel_hi:[0,1,1]
	v_pk_fma_f32 v[38:39], v[28:29], v[40:41], v[38:39] op_sel_hi:[0,1,1]
	v_pk_fma_f32 v[10:11], v[28:29], v[10:11], v[42:43] op_sel_hi:[0,1,1]
	v_pk_mul_f32 v[40:41], v[36:37], v[64:65] op_sel_hi:[0,1]
	v_pk_mul_f32 v[42:43], v[36:37], v[58:59] op_sel_hi:[0,1]
	v_pk_fma_f32 v[42:43], v[24:25], v[56:57], v[42:43] op_sel_hi:[0,1,1]
	v_pk_fma_f32 v[40:41], v[24:25], v[54:55], v[40:41] op_sel_hi:[0,1,1]
	v_pk_fma_f32 v[40:41], v[26:27], v[56:57], v[40:41] op_sel_hi:[0,1,1]
	v_pk_fma_f32 v[42:43], v[26:27], v[44:45], v[42:43] op_sel_hi:[0,1,1]
	v_pk_add_f32 v[10:11], v[32:33], v[10:11] op_sel_hi:[0,1]
	v_pk_add_f32 v[38:39], v[32:33], v[38:39] op_sel_hi:[0,1]
	v_pk_add_f32 v[42:43], v[16:17], v[42:43] op_sel_hi:[0,1]
	v_pk_add_f32 v[40:41], v[16:17], v[40:41] op_sel_hi:[0,1]
	v_pk_mul_f32 v[38:39], v[38:39], v[40:41]
	v_pk_mul_f32 v[40:41], v[10:11], v[42:43]
	v_add_u32_e32 v23, s85, v53
	v_mov_b32_e32 v10, v15
	v_mov_b32_e32 v11, v14
	ds_write_b128 v23, v[10:13]
	ds_write_b128 v23, v[38:41] offset:16
	v_lshlrev_b32_e32 v10, 16, v52
	v_mul_f32_e32 v12, v8, v10
	v_lshlrev_b32_e32 v10, 16, v49
	s_waitcnt vmcnt(2)
	s_nop 1
	v_mov_b32_e32 v0, v240
	v_mov_b32_e32 v1, v241
	v_mov_b32_e32 v2, v242
	v_mov_b32_e32 v3, v243
	v_and_b32_e32 v15, s0, v1
	v_and_b32_e32 v14, 0xffff0000, v0
	v_lshlrev_b32_e32 v23, 16, v1
	v_mul_f32_e32 v39, v9, v10
	v_lshlrev_b32_e32 v10, 16, v51
	v_pk_mov_b32 v[48:49], v[22:23], v[14:15] op_sel:[1,0]
	v_mul_f32_e32 v42, v8, v10
	v_lshlrev_b32_e32 v8, 16, v50
	v_mov_b32_e32 v13, v49
	v_mul_f32_e32 v45, v9, v8
	s_nop 0
	v_pk_mul_f32 v[50:51], v[30:31], v[12:13]
	global_load_dwordx4 v[12:15], v76, s[96:97]
	v_lshlrev_b32_e32 v40, 16, v0
	v_pk_fma_f32 v[40:41], v[30:31], v[40:41], v[50:51] op_sel:[0,0,1] op_sel_hi:[1,0,0]
	s_waitcnt vmcnt(2)
	s_nop 1
	v_mov_b32_e32 v4, v244
	v_mov_b32_e32 v5, v245
	v_mov_b32_e32 v6, v246
	v_mov_b32_e32 v7, v247
	v_and_b32_e32 v51, s0, v5
	v_and_b32_e32 v50, 0xffff0000, v4
	v_lshlrev_b32_e32 v27, 16, v5
	v_pk_mov_b32 v[50:51], v[26:27], v[50:51] op_sel:[1,0]
	v_lshlrev_b32_e32 v46, 16, v4
	v_mov_b32_e32 v43, v51
	v_pk_mul_f32 v[42:43], v[24:25], v[42:43]
	v_pk_fma_f32 v[40:41], v[28:29], v[48:49], v[40:41] op_sel_hi:[0,1,1]
	v_pk_fma_f32 v[42:43], v[24:25], v[46:47], v[42:43] op_sel:[0,0,1] op_sel_hi:[1,0,0]
	v_pk_add_f32 v[40:41], v[32:33], v[40:41] op_sel_hi:[0,1]
	v_pk_fma_f32 v[42:43], v[26:27], v[50:51], v[42:43] op_sel_hi:[0,1,1]
	v_pk_add_f32 v[42:43], v[16:17], v[42:43] op_sel_hi:[0,1]
	v_and_b32_e32 v38, 0xffff0000, v3
	v_pk_mul_f32 v[40:41], v[40:41], v[42:43]
	v_and_b32_e32 v43, 16, v2
	v_and_b32_e32 v42, 0xffff0000, v1
	v_lshlrev_b32_e32 v1, 16, v2
	v_and_b32_e32 v47, 16, v3
	v_and_b32_e32 v46, 0xffff0000, v2
	v_lshlrev_b32_e32 v53, 16, v3
	v_and_b32_e32 v3, 16, v6
	v_and_b32_e32 v2, 0xffff0000, v5
	v_mov_b32_e32 v0, v42
	v_mov_b32_e32 v4, v2
	v_pk_mul_f32 v[48:49], v[30:31], v[48:49] op_sel_hi:[0,1]
	v_pk_mul_f32 v[50:51], v[24:25], v[50:51] op_sel_hi:[0,1]
	v_pk_mov_b32 v[42:43], v[22:23], v[42:43] op_sel:[1,0]
	v_pk_mov_b32 v[2:3], v[26:27], v[2:3] op_sel:[1,0]
	v_lshlrev_b32_e32 v5, 16, v6
	v_pk_fma_f32 v[42:43], v[34:35], v[42:43], v[48:49] op_sel:[0,0,1] op_sel_hi:[0,1,0]
	v_pk_fma_f32 v[2:3], v[36:37], v[2:3], v[50:51] op_sel:[0,0,1] op_sel_hi:[0,1,0]
	v_pk_fma_f32 v[42:43], v[28:29], v[0:1], v[42:43] op_sel_hi:[0,1,1]
	v_pk_fma_f32 v[2:3], v[26:27], v[4:5], v[2:3] op_sel_hi:[0,1,1]
	v_pk_add_f32 v[42:43], v[32:33], v[42:43] op_sel_hi:[0,1]
	v_pk_add_f32 v[2:3], v[16:17], v[2:3] op_sel_hi:[0,1]
	v_pk_mul_f32 v[2:3], v[42:43], v[2:3]
	v_mov_b32_e32 v42, v53
	v_mov_b32_e32 v43, v38
	v_mov_b32_e32 v52, v46
	v_and_b32_e32 v55, 16, v7
	v_and_b32_e32 v54, 0xffff0000, v6
	v_pk_mul_f32 v[42:43], v[34:35], v[42:43] op_sel_hi:[0,1]
	v_and_b32_e32 v44, 0xffff0000, v7
	v_pk_mov_b32 v[46:47], v[0:1], v[46:47] op_sel:[1,0]
	v_lshlrev_b32_e32 v7, 16, v7
	v_mov_b32_e32 v6, v54
	v_pk_mov_b32 v[54:55], v[4:5], v[54:55] op_sel:[1,0]
	v_pk_fma_f32 v[42:43], v[30:31], v[52:53], v[42:43] op_sel_hi:[0,1,1]
	v_mov_b32_e32 v48, v7
	v_mov_b32_e32 v49, v44
	v_pk_mul_f32 v[46:47], v[34:35], v[46:47] op_sel_hi:[0,1]
	v_pk_fma_f32 v[38:39], v[28:29], v[38:39], v[42:43] op_sel_hi:[0,1,1]
	v_pk_mul_f32 v[42:43], v[36:37], v[54:55] op_sel_hi:[0,1]
	v_pk_fma_f32 v[0:1], v[30:31], v[0:1], v[46:47] op_sel_hi:[0,1,1]
	v_pk_mul_f32 v[46:47], v[36:37], v[48:49] op_sel_hi:[0,1]
	v_pk_fma_f32 v[4:5], v[24:25], v[4:5], v[42:43] op_sel_hi:[0,1,1]
	v_pk_fma_f32 v[0:1], v[28:29], v[52:53], v[0:1] op_sel_hi:[0,1,1]
	v_pk_fma_f32 v[46:47], v[24:25], v[6:7], v[46:47] op_sel_hi:[0,1,1]
	v_pk_fma_f32 v[4:5], v[26:27], v[6:7], v[4:5] op_sel_hi:[0,1,1]
	v_pk_add_f32 v[0:1], v[32:33], v[0:1] op_sel_hi:[0,1]
	v_pk_fma_f32 v[6:7], v[26:27], v[44:45], v[46:47] op_sel_hi:[0,1,1]
	v_pk_add_f32 v[4:5], v[16:17], v[4:5] op_sel_hi:[0,1]
	v_pk_add_f32 v[38:39], v[32:33], v[38:39] op_sel_hi:[0,1]
	v_pk_add_f32 v[6:7], v[16:17], v[6:7] op_sel_hi:[0,1]
	v_pk_mul_f32 v[4:5], v[0:1], v[4:5]
	v_add_u32_e32 v23, s85, v79
	v_mov_b32_e32 v0, v41
	v_mov_b32_e32 v1, v40
	v_pk_mul_f32 v[6:7], v[38:39], v[6:7]
	ds_write_b128 v23, v[0:3]
	ds_write_b128 v23, v[4:7] offset:16
	v_lshlrev_b32_e32 v1, 16, v80
	v_mul_f32_e32 v5, v78, v1
	v_lshlrev_b32_e32 v1, 16, v84
	v_lshlrev_b32_e32 v0, 16, v83
	v_mul_f32_e32 v6, v77, v1
	s_waitcnt vmcnt(1)
; #define LAS __attribute__((address_space(3)))
; template <int VAR> __device__ __forceinline__ void hyena_conv_phase(const Frame& F, const bf16* ZT, const bf16* GT, const float* conv_w, const float* conv_b, const float* skip, float* gscr, float* zscr, bf16* UT) {
;     ...
;         for (int qi = 0; qi < 8; ++qi) { const int q = t + 512 * qi; const int b = qi >> 2, p0 = (q & 2047) * 8; float cv[8], cx[8];
;             conv8(rv + b * SEQL, p0, v0, v1, v2, vb, cv); conv8(rx1 + b * SEQL, p0, b0, b1, b2, bb, cx);
;             f32x4 o0, o1;
; #pragma unroll
;             for (int e = 0; e < 4; ++e) { o0[e] = cv[e] * cx[e]; o1[e] = cv[4 + e] * cx[4 + e]; }
;             *(LAS f32x4*)(X + b * SEQL + p0) = o0; *(LAS f32x4*)(X + b * SEQL + p0 + 4) = o1; }
;         __syncthreads();
;         { gv4* pz = (gv4*)zs + t; LAS const float* x0p = X + t; LAS const float* x1p = X + SEQL + t; asm volatile("" : "+v"(x0p), "+v"(x1p), "+v"(pz));
	s_nop 1
	v_mov_b32_e32 v8, v250
	v_mov_b32_e32 v9, v251
	v_mov_b32_e32 v10, v252
	v_mov_b32_e32 v11, v253
	v_lshlrev_b32_e32 v2, 16, v8
	v_and_b32_e32 v43, s0, v9
	v_and_b32_e32 v42, 0xffff0000, v8
	v_lshlrev_b32_e32 v3, 16, v9
	s_waitcnt vmcnt(0)
	v_and_b32_e32 v45, s0, v13
	v_and_b32_e32 v44, 0xffff0000, v12
	v_lshlrev_b32_e32 v23, 16, v13
	v_lshlrev_b32_e32 v1, 16, v81
	v_pk_mov_b32 v[42:43], v[2:3], v[42:43] op_sel:[1,0]
	v_pk_mov_b32 v[44:45], v[22:23], v[44:45] op_sel:[1,0]
	v_mul_f32_e32 v0, v77, v0
	v_mul_f32_e32 v39, v78, v1
	v_mov_b32_e32 v1, v43
	v_mov_b32_e32 v7, v45
	v_lshlrev_b32_e32 v40, 16, v12
	v_pk_mul_f32 v[0:1], v[30:31], v[0:1]
	v_pk_mul_f32 v[6:7], v[24:25], v[6:7]
	v_pk_fma_f32 v[0:1], v[30:31], v[2:3], v[0:1] op_sel:[0,0,1] op_sel_hi:[1,0,0]
	v_pk_fma_f32 v[6:7], v[24:25], v[40:41], v[6:7] op_sel:[0,0,1] op_sel_hi:[1,0,0]
	v_pk_fma_f32 v[0:1], v[28:29], v[42:43], v[0:1] op_sel_hi:[0,1,1]
	v_pk_fma_f32 v[6:7], v[26:27], v[44:45], v[6:7] op_sel_hi:[0,1,1]
	v_pk_add_f32 v[0:1], v[32:33], v[0:1] op_sel_hi:[0,1]
	v_pk_add_f32 v[6:7], v[16:17], v[6:7] op_sel_hi:[0,1]
	v_pk_mul_f32 v[40:41], v[0:1], v[6:7]
	v_and_b32_e32 v1, 16, v10
	v_and_b32_e32 v0, 0xffff0000, v9
	v_and_b32_e32 v47, 16, v14
	v_and_b32_e32 v46, 0xffff0000, v13
	v_mov_b32_e32 v6, v0
	v_pk_mul_f32 v[42:43], v[30:31], v[42:43] op_sel_hi:[0,1]
	v_pk_mul_f32 v[44:45], v[24:25], v[44:45] op_sel_hi:[0,1]
	v_pk_mov_b32 v[0:1], v[2:3], v[0:1] op_sel:[1,0]
	v_pk_mov_b32 v[2:3], v[22:23], v[46:47] op_sel:[1,0]
	v_lshlrev_b32_e32 v7, 16, v10
	v_lshlrev_b32_e32 v13, 16, v14
	v_mov_b32_e32 v12, v46
	v_pk_fma_f32 v[0:1], v[34:35], v[0:1], v[42:43] op_sel:[0,0,1] op_sel_hi:[0,1,0]
	v_pk_fma_f32 v[2:3], v[36:37], v[2:3], v[44:45] op_sel:[0,0,1] op_sel_hi:[0,1,0]
	v_and_b32_e32 v9, 16, v11
	v_and_b32_e32 v8, 0xffff0000, v10
	v_pk_fma_f32 v[0:1], v[28:29], v[6:7], v[0:1] op_sel_hi:[0,1,1]
	v_pk_fma_f32 v[2:3], v[26:27], v[12:13], v[2:3] op_sel_hi:[0,1,1]
	v_and_b32_e32 v4, 0xffff0000, v11
	v_lshlrev_b32_e32 v11, 16, v11
	v_mov_b32_e32 v10, v8
	v_pk_mov_b32 v[8:9], v[6:7], v[8:9] op_sel:[1,0]
	v_pk_add_f32 v[0:1], v[32:33], v[0:1] op_sel_hi:[0,1]
	v_pk_add_f32 v[2:3], v[16:17], v[2:3] op_sel_hi:[0,1]
	v_pk_mul_f32 v[2:3], v[0:1], v[2:3]
	v_mov_b32_e32 v0, v11
	v_mov_b32_e32 v1, v4
	v_pk_mul_f32 v[8:9], v[34:35], v[8:9] op_sel_hi:[0,1]
	v_and_b32_e32 v38, 0xffff0000, v15
	v_and_b32_e32 v49, 16, v15
	v_and_b32_e32 v48, 0xffff0000, v14
	v_lshlrev_b32_e32 v15, 16, v15
	v_pk_mul_f32 v[0:1], v[34:35], v[0:1] op_sel_hi:[0,1]
	v_pk_fma_f32 v[6:7], v[30:31], v[6:7], v[8:9] op_sel_hi:[0,1,1]
	v_mov_b32_e32 v14, v48
	v_pk_mov_b32 v[48:49], v[12:13], v[48:49] op_sel:[1,0]
	v_mov_b32_e32 v42, v15
	v_mov_b32_e32 v43, v38
	v_pk_fma_f32 v[0:1], v[30:31], v[10:11], v[0:1] op_sel_hi:[0,1,1]
	v_pk_fma_f32 v[6:7], v[28:29], v[10:11], v[6:7] op_sel_hi:[0,1,1]
	v_pk_fma_f32 v[0:1], v[28:29], v[4:5], v[0:1] op_sel_hi:[0,1,1]
	v_pk_add_f32 v[4:5], v[32:33], v[6:7] op_sel_hi:[0,1]
	v_pk_mul_f32 v[6:7], v[36:37], v[48:49] op_sel_hi:[0,1]
	v_pk_mul_f32 v[8:9], v[36:37], v[42:43] op_sel_hi:[0,1]
	v_pk_fma_f32 v[8:9], v[24:25], v[14:15], v[8:9] op_sel_hi:[0,1,1]
	v_pk_fma_f32 v[6:7], v[24:25], v[12:13], v[6:7] op_sel_hi:[0,1,1]
	v_pk_fma_f32 v[6:7], v[26:27], v[14:15], v[6:7] op_sel_hi:[0,1,1]
	v_pk_fma_f32 v[8:9], v[26:27], v[38:39], v[8:9] op_sel_hi:[0,1,1]
	v_pk_add_f32 v[0:1], v[32:33], v[0:1] op_sel_hi:[0,1]
	v_pk_add_f32 v[8:9], v[16:17], v[8:9] op_sel_hi:[0,1]
	v_pk_add_f32 v[6:7], v[16:17], v[6:7] op_sel_hi:[0,1]
	v_pk_mul_f32 v[4:5], v[4:5], v[6:7]
	v_pk_mul_f32 v[6:7], v[0:1], v[8:9]
	v_add_u32_e32 v8, s85, v29
	v_mov_b32_e32 v0, v41
	v_mov_b32_e32 v1, v40
	ds_write_b128 v8, v[0:3]
	ds_write_b128 v8, v[4:7] offset:16
	v_ashrrev_i32_e32 v23, 31, v22
	v_lshlrev_b32_e32 v0, 2, v22
	v_lshl_add_u64 v[4:5], v[22:23], 4, s[0:1]
	v_add_u32_e32 v10, 0, v0
	v_add_u32_e32 v11, s85, v0
	s_waitcnt lgkmcnt(0)
	s_barrier
; #define LAS __attribute__((address_space(3)))
; __device__ __forceinline__ unsigned pk2(float lo, float hi) { unsigned r; asm("v_cvt_pk_bf16_f32 %0, %1, %2" : "=v"(r) : "v"(lo), "v"(hi)); return r; }
; template <int VAR> __device__ __forceinline__ void hyena_conv_phase(const Frame& F, const bf16* ZT, const bf16* GT, const float* conv_w, const float* conv_b, const float* skip, float* gscr, float* zscr, bf16* UT) {
;     ...
;         { gv4* pz = (gv4*)zs + t; LAS const float* x0p = X + t; LAS const float* x1p = X + SEQL + t; asm volatile("" : "+v"(x0p), "+v"(x1p), "+v"(pz));
; #pragma unroll
;           for (int g = 0; g < 8; ++g) { v4u w; w.x = pk2(x0p[512 * (4 * g)], x1p[512 * (4 * g)]); w.y = pk2(x0p[512 * (4 * g + 1)], x1p[512 * (4 * g + 1)]); w.z = pk2(x0p[512 * (4 * g + 2)], x1p[512 * (4 * g + 2)]); w.w = pk2(x0p[512 * (4 * g + 3)], x1p[512 * (4 * g + 3)]);
;               *pz = w; pz += 512; asm volatile("" : "+v"(pz)); } }
;         __syncthreads();
	ds_read2st64_b32 v[0:1], v10 offset1:8
	ds_read2st64_b32 v[2:3], v11 offset1:8
	ds_read2st64_b32 v[6:7], v10 offset0:16 offset1:24
	ds_read2st64_b32 v[8:9], v11 offset0:16 offset1:24
	s_waitcnt lgkmcnt(2)
	v_cvt_pk_bf16_f32 v0, v0, v2
	v_cvt_pk_bf16_f32 v1, v1, v3
	s_waitcnt lgkmcnt(0)
	v_cvt_pk_bf16_f32 v2, v6, v8
	v_cvt_pk_bf16_f32 v3, v7, v9
	global_store_dwordx4 v[4:5], v[0:3], off
	v_lshl_add_u64 v[4:5], v[4:5], 0, s[26:27]
	ds_read2st64_b32 v[0:1], v10 offset0:32 offset1:40
	ds_read2st64_b32 v[2:3], v11 offset0:32 offset1:40
	ds_read2st64_b32 v[6:7], v10 offset0:48 offset1:56
	ds_read2st64_b32 v[8:9], v11 offset0:48 offset1:56
	s_waitcnt lgkmcnt(2)
	v_cvt_pk_bf16_f32 v0, v0, v2
	v_cvt_pk_bf16_f32 v1, v1, v3
	s_waitcnt lgkmcnt(0)
	v_cvt_pk_bf16_f32 v2, v6, v8
	v_cvt_pk_bf16_f32 v3, v7, v9
	global_store_dwordx4 v[4:5], v[0:3], off
	v_lshl_add_u64 v[4:5], v[4:5], 0, s[26:27]
	ds_read2st64_b32 v[0:1], v10 offset0:64 offset1:72
	ds_read2st64_b32 v[2:3], v11 offset0:64 offset1:72
	ds_read2st64_b32 v[6:7], v10 offset0:80 offset1:88
	ds_read2st64_b32 v[8:9], v11 offset0:80 offset1:88
	s_waitcnt lgkmcnt(2)
	v_cvt_pk_bf16_f32 v0, v0, v2
	v_cvt_pk_bf16_f32 v1, v1, v3
	s_waitcnt lgkmcnt(0)
	v_cvt_pk_bf16_f32 v2, v6, v8
	v_cvt_pk_bf16_f32 v3, v7, v9
	global_store_dwordx4 v[4:5], v[0:3], off
	v_lshl_add_u64 v[4:5], v[4:5], 0, s[26:27]
	ds_read2st64_b32 v[0:1], v10 offset0:96 offset1:104
	ds_read2st64_b32 v[2:3], v11 offset0:96 offset1:104
	ds_read2st64_b32 v[6:7], v10 offset0:112 offset1:120
	ds_read2st64_b32 v[8:9], v11 offset0:112 offset1:120
	s_waitcnt lgkmcnt(2)
	v_cvt_pk_bf16_f32 v0, v0, v2
	v_cvt_pk_bf16_f32 v1, v1, v3
	s_waitcnt lgkmcnt(0)
	v_cvt_pk_bf16_f32 v2, v6, v8
	v_cvt_pk_bf16_f32 v3, v7, v9
	global_store_dwordx4 v[4:5], v[0:3], off
	v_lshl_add_u64 v[4:5], v[4:5], 0, s[26:27]
	ds_read2st64_b32 v[0:1], v10 offset0:128 offset1:136
	ds_read2st64_b32 v[2:3], v11 offset0:128 offset1:136
	ds_read2st64_b32 v[6:7], v10 offset0:144 offset1:152
	ds_read2st64_b32 v[8:9], v11 offset0:144 offset1:152
	s_waitcnt lgkmcnt(2)
	v_cvt_pk_bf16_f32 v0, v0, v2
	v_cvt_pk_bf16_f32 v1, v1, v3
	s_waitcnt lgkmcnt(0)
	v_cvt_pk_bf16_f32 v2, v6, v8
	v_cvt_pk_bf16_f32 v3, v7, v9
	global_store_dwordx4 v[4:5], v[0:3], off
	v_lshl_add_u64 v[4:5], v[4:5], 0, s[26:27]
	ds_read2st64_b32 v[0:1], v10 offset0:160 offset1:168
	ds_read2st64_b32 v[2:3], v11 offset0:160 offset1:168
	ds_read2st64_b32 v[6:7], v10 offset0:176 offset1:184
	ds_read2st64_b32 v[8:9], v11 offset0:176 offset1:184
	s_waitcnt lgkmcnt(2)
	v_cvt_pk_bf16_f32 v0, v0, v2
	v_cvt_pk_bf16_f32 v1, v1, v3
	s_waitcnt lgkmcnt(0)
	v_cvt_pk_bf16_f32 v2, v6, v8
	v_cvt_pk_bf16_f32 v3, v7, v9
	global_store_dwordx4 v[4:5], v[0:3], off
	v_lshl_add_u64 v[4:5], v[4:5], 0, s[26:27]
	ds_read2st64_b32 v[0:1], v10 offset0:192 offset1:200
	ds_read2st64_b32 v[2:3], v11 offset0:192 offset1:200
	ds_read2st64_b32 v[6:7], v10 offset0:208 offset1:216
	ds_read2st64_b32 v[8:9], v11 offset0:208 offset1:216
	s_waitcnt lgkmcnt(2)
	v_cvt_pk_bf16_f32 v0, v0, v2
	v_cvt_pk_bf16_f32 v1, v1, v3
	s_waitcnt lgkmcnt(0)
	v_cvt_pk_bf16_f32 v2, v6, v8
	v_cvt_pk_bf16_f32 v3, v7, v9
	global_store_dwordx4 v[4:5], v[0:3], off
	v_lshl_add_u64 v[4:5], v[4:5], 0, s[26:27]
	ds_read2st64_b32 v[0:1], v10 offset0:224 offset1:232
	ds_read2st64_b32 v[2:3], v11 offset0:224 offset1:232
	ds_read2st64_b32 v[6:7], v10 offset0:240 offset1:248
	ds_read2st64_b32 v[8:9], v11 offset0:240 offset1:248
	s_waitcnt lgkmcnt(2)
	v_cvt_pk_bf16_f32 v0, v0, v2
	v_cvt_pk_bf16_f32 v1, v1, v3
	s_waitcnt lgkmcnt(0)
	v_cvt_pk_bf16_f32 v2, v6, v8
	v_cvt_pk_bf16_f32 v3, v7, v9
	global_store_dwordx4 v[4:5], v[0:3], off
	s_nop 1
	v_lshl_add_u64 v[0:1], v[4:5], 0, s[26:27]
	s_barrier
	s_branch .LBB0_325
